# attention softmax row-sum accumulation via v_pk_add_f32 pairs (29->16 VALU adds per step) + redundant canonicalising v_max removed
# baseline (speedup 1.0000x reference)
; __device__ __forceinline__ void attn_item(const bf16_t* __restrict__ Qb, const bf16_t* __restrict__ Kh, const bf16_t* __restrict__ Vh, const bf16_t* __restrict__ Zb, ...
;   int tid_ = MYTID(wid_s); asm volatile("" : "+v"(tid_)); const int tid = tid_, wid = tid >> 6, lane = tid & 63, r32 = lane & 31, hi = lane >> 5;
;   constexpr int SLOT = 32768, KOFF = 16384, WSOFF = 3 * SLOT;
;   float* ws = (float*)(lds + WSOFF) + wid * 64; float* al_l = ws + 32;
;   float m_reg = 0.f, l_reg = 0; f32x16 o[4] = {}; bf16x8 qr[8]; f32x16 negm = f32x16{}; asm volatile("" : "+v"(negm));
;   const bf16_t* Qw = Qb + (long)(wid * QBLK + r32) * LDQ + hi * 8;
;   float qn2 = 0.f;
;   {
;     u32x4 qw[8];
; #pragma unroll
;     for (int d0 = 0; d0 < 8; ++d0) qw[d0] = *reinterpret_cast<const u32x4*>(Qw + d0 * 16);
;     float ss = 0.f;
; #pragma unroll
;     for (int d0 = 0; d0 < 8; ++d0) { const float a0 = bflo(qw[d0].x), a1 = bfhi(qw[d0].x), a2 = bflo(qw[d0].y), a3 = bfhi(qw[d0].y), a4 = bflo(qw[d0].z), a5 = bfhi(qw[d0].z), a6 = bflo(qw[d0].w), a7 = bfhi(qw[d0].w);
;       ss += (a0 * a0 + a1 * a1) + (a2 * a2 + a3 * a3) + (a4 * a4 + a5 * a5) + (a6 * a6 + a7 * a7); }
;     { auto rr = __builtin_amdgcn_permlane32_swap(__float_as_uint(ss), __float_as_uint(ss), false, false); ss = __uint_as_float(rr[0]) + __uint_as_float(rr[1]); }
;     const float rstd = __builtin_amdgcn_rsqf(ss * (1.0f / 128.0f) + NORM_EPS) * (SCALE * 1.4426950408889634f);
;     const int hq = lane_id_asm() >> 5;
;     const int spos = qpos0 + wid * QBLK + r32; const float prow = (float)(spos >> 6), pcol = (float)(spos & 63);
; #pragma unroll
;     for (int bb = 0; bb < 4; ++bb) { const int d1 = (bb & 1) + 4 * (bb >> 1), d2 = d1 + 2;
;       const float pos = (bb < 2) ? prow : pcol; const float* g1p = qg + d1 * 16 + hq * 8; const float* g2p = qg + d2 * 16 + hq * 8;
; __global__ void __launch_bounds__(512, 2) fwd_megakernel(Args a) {
;     ...
;     const int xx = it & 7, rest = it >> 3, bk = xx >> 1, qb = (xx & 1) * 32 + (rest & 31), hq = rest >> 5, kvh = bk & 1, h = kvh * 4 + hq, b = bk >> 1;
;     const long row0 = (long)b * SEQ + qb * 256;
;     att::attn_item(P1 + row0 * LDP + C_Q + h * 128, P1 + (long)b * SEQ * LDP + C_K + kvh * 128, P1 + (long)b * SEQ * LDP + C_V + kvh * 128,
;                    P1 + row0 * LDP + C_ZA + h * 128, AF + row0 * LDAF + h * 128, SEQ, (char*)lds, wid_s, a.in[3], qb * 256, kmaxg);
.LBB0_452:
	s_lshl_b32 s0, s70, 5
	s_and_b32 s0, s0, 32
	s_bfe_u32 s7, s70, 0x50003
	s_or_b32 s7, s0, s7
	s_lshl_b32 s0, s70, 12
	s_and_b32 s0, s0, 0x4000
	s_lshl_b32 s7, s7, 8
	s_bfe_u32 s1, s70, 0x10001
	s_or_b32 s71, s7, s0
	s_bfe_u32 s6, s54, 0x1000e
	s_lshl_b32 s8, s1, 8
	s_mul_i32 s9, s71, 0x2080
	s_add_u32 s9, s42, s9
	s_addc_u32 s36, s43, 0
	s_ashr_i32 s24, s70, 1
	s_lshl_b32 s1, s1, 9
	s_and_b32 s24, s24, 0xffffff80
	s_add_i32 s24, s1, s24
	s_ashr_i32 s25, s24, 31
	s_lshl_b64 s[26:27], s[24:25], 1
	s_add_u32 s24, s9, s26
	v_mbcnt_lo_u32_b32 v0, -1, 0
	v_mbcnt_hi_u32_b32 v0, -1, v0
	s_addc_u32 s25, s36, s27
	v_add_u32_e32 v186, s33, v0
	v_mov_b64_e32 v[2:3], s[24:25]
	v_ashrrev_i32_e32 v0, 1, v186
	v_and_b32_e32 v4, 0xffffffe0, v0
	v_bfi_b32 v0, s57, v0, v186
	v_lshrrev_b32_e32 v188, 1, v186
	v_mad_i64_i32 v[2:3], s[36:37], v0, s51, v[2:3]
	v_and_b32_e32 v212, 16, v188
	v_mov_b32_e32 v213, v1
	v_mov_b32_e32 v16, v1
	v_mov_b32_e32 v17, v1
	v_mov_b32_e32 v18, v1
	v_mov_b32_e32 v19, v1
	v_mov_b32_e32 v20, v1
	v_mov_b32_e32 v21, v1
	v_mov_b32_e32 v22, v1
	v_mov_b32_e32 v23, v1
	v_mov_b32_e32 v24, v1
	v_mov_b32_e32 v25, v1
	v_mov_b32_e32 v26, v1
	v_mov_b32_e32 v27, v1
	v_mov_b32_e32 v28, v1
	v_mov_b32_e32 v29, v1
	v_mov_b32_e32 v30, v1
	v_mov_b32_e32 v31, v1
	v_lshl_add_u64 v[2:3], v[2:3], 0, v[212:213]
	global_load_dwordx4 v[36:39], v[2:3], off
	global_load_dwordx4 v[44:47], v[2:3], off offset:32
	global_load_dwordx4 v[40:43], v[2:3], off offset:64
	global_load_dwordx4 v[48:51], v[2:3], off offset:96
	global_load_dwordx4 v[52:55], v[2:3], off offset:128
	global_load_dwordx4 v[60:63], v[2:3], off offset:160
	global_load_dwordx4 v[56:59], v[2:3], off offset:192
	global_load_dwordx4 v[64:67], v[2:3], off offset:224
	v_mbcnt_lo_u32_b32 v0, -1, 0
	v_mbcnt_hi_u32_b32 v0, -1, v0
	v_and_b32_e32 v187, 31, v186
	v_ashrrev_i32_e32 v0, 2, v0
	v_and_b32_e32 v78, -8, v0
	v_or_b32_e32 v69, 1, v78
	v_cvt_f32_i32_e32 v69, v69
	v_cvt_f32_i32_e32 v6, v78
	v_or_b32_e32 v2, s7, v187
	s_waitcnt vmcnt(22)
	v_add_u32_e32 v136, v2, v4
	v_mul_f32_e32 v69, 0xbed49a78, v69
	v_exp_f32_e32 v69, v69
	v_mul_f32_e32 v6, 0xbed49a78, v6
	v_ashrrev_i32_e32 v2, 6, v136
	v_exp_f32_e32 v68, v6
	v_mul_f32_e32 v138, 0.15915494, v69
	v_or_b32_e32 v69, 2, v78
	s_waitcnt vmcnt(20)
	v_cvt_f32_i32_e32 v145, v2
	v_cvt_f32_i32_e32 v69, v69
	v_ashrrev_i32_e32 v79, 31, v78
	v_lshl_add_u64 v[14:15], v[78:79], 2, s[18:19]
	global_load_dwordx4 v[10:13], v[14:15], off
	global_load_dwordx4 v[2:5], v[14:15], off offset:16
	global_load_dwordx4 v[32:35], v[14:15], off offset:128
	global_load_dwordx4 v[6:9], v[14:15], off offset:144
	v_mul_f32_e32 v137, 0.15915494, v68
	v_mul_f32_e32 v68, v137, v145
	v_mul_f32_e32 v69, 0xbed49a78, v69
	v_floor_f32_e32 v68, v68
	v_exp_f32_e32 v69, v69
	v_fma_f32 v68, v137, v145, -v68
	v_sin_f32_e32 v104, v68
	v_cos_f32_e32 v105, v68
	v_mul_f32_e32 v68, v138, v145
	v_floor_f32_e32 v68, v68
	v_fma_f32 v68, v138, v145, -v68
	v_mul_f32_e32 v139, 0.15915494, v69
	v_sin_f32_e32 v83, v68
	v_cos_f32_e32 v82, v68
	v_or_b32_e32 v68, 3, v78
	v_mul_f32_e32 v69, v139, v145
	v_cvt_f32_i32_e32 v68, v68
	v_floor_f32_e32 v69, v69
	v_fma_f32 v69, v139, v145, -v69
	v_sin_f32_e32 v106, v69
	v_cos_f32_e32 v107, v69
	v_or_b32_e32 v69, 4, v78
	v_cvt_f32_i32_e32 v69, v69
	v_mul_f32_e32 v68, 0xbed49a78, v68
	v_exp_f32_e32 v68, v68
	v_or_b32_e32 v0, 7, v0
	v_mul_f32_e32 v69, 0xbed49a78, v69
	v_exp_f32_e32 v69, v69
	v_mul_f32_e32 v140, 0.15915494, v68
	v_mul_f32_e32 v68, v140, v145
	v_floor_f32_e32 v68, v68
	v_fma_f32 v68, v140, v145, -v68
	v_mul_f32_e32 v141, 0.15915494, v69
	v_sin_f32_e32 v97, v68
	v_cos_f32_e32 v96, v68
	v_or_b32_e32 v68, 5, v78
	v_mul_f32_e32 v69, v141, v145
	v_cvt_f32_i32_e32 v68, v68
	v_floor_f32_e32 v69, v69
	v_fma_f32 v69, v141, v145, -v69
	v_sin_f32_e32 v108, v69
	v_cos_f32_e32 v109, v69
	v_or_b32_e32 v69, 6, v78
	v_cvt_f32_i32_e32 v69, v69
	v_mul_f32_e32 v68, 0xbed49a78, v68
	v_exp_f32_e32 v68, v68
	v_cvt_f32_i32_e32 v0, v0
	v_mul_f32_e32 v69, 0xbed49a78, v69
	v_exp_f32_e32 v69, v69
	v_mul_f32_e32 v142, 0.15915494, v68
	v_mul_f32_e32 v68, v142, v145
	v_floor_f32_e32 v68, v68
	v_fma_f32 v68, v142, v145, -v68
	v_mul_f32_e32 v143, 0.15915494, v69
	v_mul_f32_e32 v0, 0xbed49a78, v0
	v_sin_f32_e32 v101, v68
	v_cos_f32_e32 v100, v68
	v_mul_f32_e32 v68, v143, v145
	v_exp_f32_e32 v0, v0
	v_floor_f32_e32 v68, v68
	v_fma_f32 v68, v143, v145, -v68
	v_sin_f32_e32 v110, v68
	v_cos_f32_e32 v111, v68
	v_add_u32_e32 v68, 16, v78
	v_mul_f32_e32 v144, 0.15915494, v0
	v_cvt_f32_i32_e32 v68, v68
	v_mul_f32_e32 v0, v144, v145
	v_floor_f32_e32 v0, v0
	v_fma_f32 v0, v144, v145, -v0
	v_sin_f32_e32 v99, v0
	v_cos_f32_e32 v98, v0
	v_mul_f32_e32 v0, 0xbed49a78, v68
	s_waitcnt vmcnt(5)
; __device__ __forceinline__ float bflo(unsigned w) { return __uint_as_float(w << 16); }
; __device__ __forceinline__ float bfhi(unsigned w) { return __uint_as_float(w & 0xffff0000u); }
; __device__ __forceinline__ void attn_item(const bf16_t* __restrict__ Qb, const bf16_t* __restrict__ Kh, const bf16_t* __restrict__ Vh, const bf16_t* __restrict__ Zb, ...
;     ...
;     float ss = 0.f;
; #pragma unroll
;     for (int d0 = 0; d0 < 8; ++d0) { const float a0 = bflo(qw[d0].x), a1 = bfhi(qw[d0].x), a2 = bflo(qw[d0].y), a3 = bfhi(qw[d0].y), a4 = bflo(qw[d0].z), a5 = bfhi(qw[d0].z), a6 = bflo(qw[d0].w), a7 = bfhi(qw[d0].w);
;       ss += (a0 * a0 + a1 * a1) + (a2 * a2 + a3 * a3) + (a4 * a4 + a5 * a5) + (a6 * a6 + a7 * a7); }
	v_lshlrev_b32_e32 v93, 16, v57
	v_and_b32_e32 v91, 0xffff0000, v57
	v_and_b32_e32 v155, 0xffff0000, v43
	v_and_b32_e32 v157, 0xffff0000, v42
	v_exp_f32_e32 v79, v0
	v_mov_b32_e32 v94, v93
	v_mov_b32_e32 v95, v91
	v_mul_f32_e32 v0, v91, v91
	v_lshlrev_b32_e32 v113, 16, v49
	v_and_b32_e32 v123, 0xffff0000, v49
	v_lshlrev_b32_e32 v57, 16, v43
	v_lshlrev_b32_e32 v49, 16, v42
	v_mov_b32_e32 v42, v155
	v_mov_b32_e32 v43, v157
	v_pk_fma_f32 v[150:151], v[94:95], v[94:95], v[0:1] op_sel_hi:[1,1,0]
	v_lshlrev_b32_e32 v103, 16, v56
	v_and_b32_e32 v95, 0xffff0000, v56
	v_lshlrev_b32_e32 v125, 16, v48
	v_and_b32_e32 v117, 0xffff0000, v48
	v_lshlrev_b32_e32 v56, 16, v39
	v_and_b32_e32 v154, 0xffff0000, v39
	v_lshlrev_b32_e32 v48, 16, v38
	v_and_b32_e32 v156, 0xffff0000, v38
	v_mov_b32_e32 v38, v57
	v_mov_b32_e32 v39, v49
	v_pk_mul_f32 v[42:43], v[42:43], v[42:43]
	v_and_b32_e32 v159, 0xffff0000, v41
	v_pk_fma_f32 v[38:39], v[38:39], v[38:39], v[42:43]
	v_lshlrev_b32_e32 v43, 16, v41
	v_and_b32_e32 v41, 0xffff0000, v40
	v_and_b32_e32 v118, 0xffff0000, v47
	v_lshlrev_b32_e32 v161, 16, v40
	v_mov_b32_e32 v162, v41
	v_mov_b32_e32 v163, v159
	v_and_b32_e32 v70, 0xffff0000, v63
	v_lshlrev_b32_e32 v72, 16, v62
	v_and_b32_e32 v62, 0xffff0000, v62
	v_lshlrev_b32_e32 v114, 16, v47
	v_and_b32_e32 v120, 0xffff0000, v46
	v_lshlrev_b32_e32 v42, 16, v37
	v_and_b32_e32 v158, 0xffff0000, v37
	v_lshlrev_b32_e32 v160, 16, v36
	v_and_b32_e32 v40, 0xffff0000, v36
	v_mov_b32_e32 v36, v161
	v_mov_b32_e32 v37, v43
	v_pk_mul_f32 v[162:163], v[162:163], v[162:163]
	v_mov_b32_e32 v164, v154
	v_mov_b32_e32 v165, v118
	v_lshlrev_b32_e32 v68, 16, v63
	v_mov_b32_e32 v74, v70
	v_mov_b32_e32 v75, v62
	v_lshlrev_b32_e32 v126, 16, v46
	v_and_b32_e32 v122, 0xffff0000, v45
	v_pk_fma_f32 v[36:37], v[36:37], v[36:37], v[162:163]
	v_mov_b32_e32 v162, v56
	v_mov_b32_e32 v163, v114
	v_pk_mul_f32 v[164:165], v[164:165], v[164:165]
	v_mov_b32_e32 v166, v156
	v_mov_b32_e32 v167, v120
	s_waitcnt vmcnt(4)
	v_lshlrev_b32_e32 v69, 16, v67
	v_and_b32_e32 v71, 0xffff0000, v67
	v_lshlrev_b32_e32 v73, 16, v66
	v_and_b32_e32 v63, 0xffff0000, v66
	v_mov_b32_e32 v66, v68
	v_mov_b32_e32 v67, v72
	v_pk_mul_f32 v[74:75], v[74:75], v[74:75]
	v_lshlrev_b32_e32 v112, 16, v45
	v_and_b32_e32 v116, 0xffff0000, v44
	v_pk_fma_f32 v[162:163], v[162:163], v[162:163], v[164:165]
	v_mov_b32_e32 v164, v48
	v_mov_b32_e32 v165, v126
	v_pk_mul_f32 v[166:167], v[166:167], v[166:167]
	v_mov_b32_e32 v168, v158
	v_mov_b32_e32 v169, v122
	v_pk_fma_f32 v[80:81], v[66:67], v[66:67], v[74:75]
	v_and_b32_e32 v66, 0xffff0000, v61
	v_lshlrev_b32_e32 v76, 16, v60
	v_and_b32_e32 v60, 0xffff0000, v60
	v_lshlrev_b32_e32 v124, 16, v44
	v_pk_fma_f32 v[164:165], v[164:165], v[164:165], v[166:167]
	v_mov_b32_e32 v166, v42
	v_mov_b32_e32 v167, v112
	v_pk_mul_f32 v[168:169], v[168:169], v[168:169]
	v_mov_b32_e32 v170, v40
	v_mov_b32_e32 v171, v116
	v_lshlrev_b32_e32 v74, 16, v61
	v_mov_b32_e32 v84, v60
	v_mov_b32_e32 v85, v66
	v_pk_fma_f32 v[166:167], v[166:167], v[166:167], v[168:169]
	v_mov_b32_e32 v168, v160
	v_mov_b32_e32 v169, v124
	v_pk_mul_f32 v[170:171], v[170:171], v[170:171]
	v_lshlrev_b32_e32 v75, 16, v65
	v_and_b32_e32 v67, 0xffff0000, v65
	v_lshlrev_b32_e32 v77, 16, v64
	v_and_b32_e32 v61, 0xffff0000, v64
	v_mov_b32_e32 v64, v76
	v_mov_b32_e32 v65, v74
	v_pk_mul_f32 v[84:85], v[84:85], v[84:85]
	v_pk_fma_f32 v[168:169], v[168:169], v[168:169], v[170:171]
	v_pk_fma_f32 v[64:65], v[64:65], v[64:65], v[84:85]
	v_lshlrev_b32_e32 v92, 16, v53
	v_and_b32_e32 v90, 0xffff0000, v53
	v_lshlrev_b32_e32 v102, 16, v52
	v_and_b32_e32 v94, 0xffff0000, v52
	v_mov_b32_e32 v52, v103
	v_mov_b32_e32 v53, v95
	v_mul_f32_e32 v0, v95, v95
	v_pk_add_f32 v[166:167], v[168:169], v[166:167]
	v_pk_add_f32 v[64:65], v[64:65], v[64:65] op_sel:[0,1] op_sel_hi:[1,0]
	v_and_b32_e32 v87, 0xffff0000, v58
	v_and_b32_e32 v86, 0xffff0000, v54
	v_pk_fma_f32 v[52:53], v[52:53], v[52:53], v[0:1] op_sel_hi:[1,1,0]
	v_and_b32_e32 v119, 0xffff0000, v51
	v_mov_b32_e32 v46, v113
	v_mov_b32_e32 v47, v123
	v_mul_f32_e32 v0, v123, v123
	v_pk_add_f32 v[36:37], v[36:37], v[36:37] op_sel:[0,1] op_sel_hi:[1,0]
	v_pk_add_f32 v[164:165], v[164:165], v[166:167]
	v_pk_add_f32 v[64:65], v[80:81], v[64:65] op_sel:[1,0] op_sel_hi:[0,1]
	v_lshlrev_b32_e32 v89, 16, v58
	v_lshlrev_b32_e32 v88, 16, v54
	v_lshlrev_b32_e32 v115, 16, v51
	v_and_b32_e32 v121, 0xffff0000, v50
	v_pk_fma_f32 v[46:47], v[46:47], v[46:47], v[0:1] op_sel_hi:[1,1,0]
	v_mov_b32_e32 v44, v125
	v_mov_b32_e32 v45, v117
	v_mul_f32_e32 v0, v117, v117
	v_pk_add_f32 v[36:37], v[38:39], v[36:37] op_sel:[1,0] op_sel_hi:[0,1]
	v_pk_add_f32 v[162:163], v[162:163], v[164:165]
	v_pk_mov_b32 v[164:165], v[118:119], v[86:87] op_sel:[1,0]
	v_pk_add_f32 v[64:65], v[80:81], v[64:65]
	v_lshlrev_b32_e32 v85, 16, v59
	v_lshlrev_b32_e32 v84, 16, v55
	v_and_b32_e32 v81, 0xffff0000, v59
	v_and_b32_e32 v80, 0xffff0000, v55
	v_pk_mul_f32 v[54:55], v[92:93], v[92:93]
	v_pk_mul_f32 v[58:59], v[90:91], v[90:91]
	v_lshlrev_b32_e32 v127, 16, v50
	v_pk_fma_f32 v[44:45], v[44:45], v[44:45], v[0:1] op_sel_hi:[1,1,0]
	v_pk_add_f32 v[36:37], v[38:39], v[36:37]
	v_pk_add_f32 v[38:39], v[162:163], v[162:163] op_sel:[0,1] op_sel_hi:[1,0]
	v_pk_mov_b32 v[162:163], v[114:115], v[88:89] op_sel:[1,0]
	v_pk_mul_f32 v[164:165], v[164:165], v[164:165]
	v_pk_mov_b32 v[166:167], v[120:121], v[94:95] op_sel:[1,0]
	v_pk_fma_f32 v[162:163], v[162:163], v[162:163], v[164:165]
	v_pk_mov_b32 v[164:165], v[126:127], v[102:103] op_sel:[1,0]
	v_pk_mul_f32 v[166:167], v[166:167], v[166:167]
	v_mov_b32_e32 v45, v54
	v_mov_b32_e32 v47, v58
	v_pk_mul_f32 v[146:147], v[84:85], v[84:85]
	v_pk_mul_f32 v[148:149], v[80:81], v[80:81]
	v_pk_fma_f32 v[164:165], v[164:165], v[164:165], v[166:167]
	v_pk_add_f32 v[44:45], v[44:45], v[46:47]
	v_mov_b32_e32 v39, v146
	v_pk_add_f32 v[44:45], v[164:165], v[44:45]
	v_mov_b32_e32 v37, v148
	v_pk_add_f32 v[44:45], v[162:163], v[44:45]
	v_pk_add_f32 v[36:37], v[38:39], v[36:37]
	v_pk_mul_f32 v[132:133], v[74:75], v[74:75]
	v_pk_add_f32 v[36:37], v[36:37], v[44:45]
	v_mov_b32_e32 v44, v81
	v_mov_b32_e32 v45, v63
	v_pk_mul_f32 v[134:135], v[66:67], v[66:67]
	v_mov_b32_e32 v38, v85
	v_mov_b32_e32 v39, v73
	v_pk_mul_f32 v[44:45], v[44:45], v[44:45]
	v_mov_b32_e32 v46, v87
	v_mov_b32_e32 v47, v61
	v_pk_fma_f32 v[38:39], v[38:39], v[38:39], v[44:45]
	v_mov_b32_e32 v44, v89
	v_mov_b32_e32 v45, v77
	v_pk_mul_f32 v[46:47], v[46:47], v[46:47]
	v_mov_b32_e32 v53, v133
	v_mov_b32_e32 v151, v135
	v_pk_mul_f32 v[128:129], v[68:69], v[68:69]
	v_pk_mul_f32 v[130:131], v[70:71], v[70:71]
	v_pk_add_f32 v[36:37], v[36:37], v[36:37] op_sel:[0,1] op_sel_hi:[1,0]
	v_pk_fma_f32 v[44:45], v[44:45], v[44:45], v[46:47]
	v_pk_add_f32 v[46:47], v[52:53], v[150:151]
	v_mov_b32_e32 v37, v129
	v_pk_add_f32 v[44:45], v[44:45], v[46:47]
	v_mov_b32_e32 v65, v131
	v_pk_add_f32 v[38:39], v[38:39], v[44:45]
	v_pk_add_f32 v[36:37], v[36:37], v[64:65]
	s_waitcnt vmcnt(2)
; __device__ __forceinline__ int lane_id_asm() { int r; asm volatile("v_mbcnt_lo_u32_b32 %0, -1, 0\n\tv_mbcnt_hi_u32_b32 %0, -1, %0" : "=v"(r)); return r; }
; __device__ __forceinline__ float bflo(unsigned w) { return __uint_as_float(w << 16); }
; __device__ __forceinline__ void attn_item(const bf16_t* __restrict__ Qb, const bf16_t* __restrict__ Kh, const bf16_t* __restrict__ Vh, const bf16_t* __restrict__ Zb, ...
;     ...
;     { auto rr = __builtin_amdgcn_permlane32_swap(__float_as_uint(ss), __float_as_uint(ss), false, false); ss = __uint_as_float(rr[0]) + __uint_as_float(rr[1]); }
;     const float rstd = __builtin_amdgcn_rsqf(ss * (1.0f / 128.0f) + NORM_EPS) * (SCALE * 1.4426950408889634f);
;     const int hq = lane_id_asm() >> 5;
;     const int spos = qpos0 + wid * QBLK + r32; const float prow = (float)(spos >> 6), pcol = (float)(spos & 63);
; #pragma unroll
;     for (int bb = 0; bb < 4; ++bb) { const int d1 = (bb & 1) + 4 * (bb >> 1), d2 = d1 + 2;
;       const float pos = (bb < 2) ? prow : pcol; const float* g1p = qg + d1 * 16 + hq * 8; const float* g2p = qg + d2 * 16 + hq * 8;
;       const f32x4 g1a = *(const f32x4*)g1p, g1b = *(const f32x4*)(g1p + 4), g2a = *(const f32x4*)g2p, g2b = *(const f32x4*)(g2p + 4);
;       float o1[8], o2[8];
; #pragma unroll
;       for (int e = 0; e < 8; ++e) { const unsigned w1 = (e < 2) ? qw[d1].x : (e < 4) ? qw[d1].y : (e < 6) ? qw[d1].z : qw[d1].w, w2 = (e < 2) ? qw[d2].x : (e < 4) ? qw[d2].y : (e < 6) ? qw[d2].z : qw[d2].w;
;         const float x1 = (e & 1) ? bfhi(w1) : bflo(w1), x2 = (e & 1) ? bfhi(w2) : bflo(w2); const float ga = (e < 4) ? g1a[e & 3] : g1b[e & 3], gb = (e < 4) ? g2a[e & 3] : g2b[e & 3];
;         const int fi = (d1 & 1) * 16 + hq * 8 + e; float rev = pos * (__builtin_amdgcn_exp2f(-(float)fi * (13.287712379549449f / 32.0f)) * 0.15915494309189535f); rev -= floorf(rev);
;         const float sn = sin_rev(rev), cs = cos_rev(rev), y1 = x1 * rstd * ga, y2 = x2 * rstd * gb; o1[e] = y1 * cs - y2 * sn; o2[e] = y2 * cs + y1 * sn; }
; #pragma unroll
;       for (int e = 0; e < 8; ++e) qn2 += o1[e] * o1[e] + o2[e] * o2[e];
;       u32x4 p1 = {cvtpk(o1[0], o1[1]), cvtpk(o1[2], o1[3]), cvtpk(o1[4], o1[5]), cvtpk(o1[6], o1[7])}, p2 = {cvtpk(o2[0], o2[1]), cvtpk(o2[2], o2[3]), cvtpk(o2[4], o2[5]), cvtpk(o2[6], o2[7])};
;       qr[d1] = *reinterpret_cast<bf16x8*>(&p1); qr[d2] = *reinterpret_cast<bf16x8*>(&p2); }
	v_mov_b32_e32 v50, v2
	v_pk_add_f32 v[36:37], v[36:37], v[38:39]
	v_mov_b32_e32 v128, v12
	v_pk_add_f32 v[36:37], v[36:37], v[36:37] op_sel:[0,1] op_sel_hi:[1,0]
	s_waitcnt vmcnt(1)
	v_mov_b32_e32 v129, v34
	v_mov_b32_e32 v0, v36
	s_nop 1
	v_permlane32_swap_b32_e32 v36, v0
	v_add_f32_e32 v0, v36, v0
	v_fmamk_f32 v0, v0, 0x3c000000, v217
	v_rsq_f32_e32 v0, v0
	v_mov_b32_e32 v36, v10
	v_mov_b32_e32 v37, v32
	v_mov_b32_e32 v32, v11
	v_mul_f32_e32 v0, 0x3e0293ee, v0
	v_pk_mul_f32 v[38:39], v[0:1], v[160:161] op_sel_hi:[0,1]
	v_pk_mul_f32 v[38:39], v[36:37], v[38:39]
	v_mov_b32_e32 v36, v105
	v_mov_b32_e32 v37, v104
	v_mul_f32_e32 v2, v39, v104
	v_pk_mul_f32 v[40:41], v[0:1], v[40:41] op_sel_hi:[0,1]
	v_pk_fma_f32 v[36:37], v[38:39], v[36:37], v[2:3] op_sel_hi:[1,1,0] neg_lo:[0,0,1] neg_hi:[0,0,1]
	v_mul_f32_e32 v2, v39, v105
	v_pk_mul_f32 v[10:11], v[32:33], v[40:41]
	v_pk_fma_f32 v[38:39], v[38:39], v[104:105], v[2:3] op_sel_hi:[1,1,0]
	v_mul_f32_e32 v2, v11, v83
	v_pk_fma_f32 v[32:33], v[10:11], v[82:83], v[2:3] op_sel_hi:[1,1,0] neg_lo:[0,0,1] neg_hi:[0,0,1]
	v_mov_b32_e32 v40, v83
	v_mov_b32_e32 v41, v82
	v_mul_f32_e32 v2, v11, v82
	v_pk_fma_f32 v[40:41], v[10:11], v[40:41], v[2:3] op_sel_hi:[1,1,0]
	v_pk_mul_f32 v[10:11], v[0:1], v[42:43] op_sel_hi:[0,1]
	v_pk_mul_f32 v[10:11], v[128:129], v[10:11]
	v_mov_b32_e32 v42, v107
	v_mov_b32_e32 v43, v106
	v_mul_f32_e32 v2, v11, v106
	v_pk_fma_f32 v[42:43], v[10:11], v[42:43], v[2:3] op_sel_hi:[1,1,0] neg_lo:[0,0,1] neg_hi:[0,0,1]
	v_mul_f32_e32 v2, v11, v107
	v_pk_fma_f32 v[44:45], v[10:11], v[106:107], v[2:3] op_sel_hi:[1,1,0]
	v_pk_mul_f32 v[10:11], v[0:1], v[158:159] op_sel_hi:[0,1]
	v_mov_b32_e32 v34, v13
	v_pk_mul_f32 v[10:11], v[34:35], v[10:11]
	v_mov_b32_e32 v12, v97
	v_mul_f32_e32 v2, v11, v97
	v_pk_fma_f32 v[34:35], v[10:11], v[96:97], v[2:3] op_sel_hi:[1,1,0] neg_lo:[0,0,1] neg_hi:[0,0,1]
	v_mov_b32_e32 v13, v96
	v_mul_f32_e32 v2, v11, v96
	s_waitcnt vmcnt(0)
	v_mov_b32_e32 v51, v6
	v_pk_fma_f32 v[46:47], v[10:11], v[12:13], v[2:3] op_sel_hi:[1,1,0]
	v_pk_mul_f32 v[10:11], v[0:1], v[48:49] op_sel_hi:[0,1]
	v_pk_mul_f32 v[10:11], v[50:51], v[10:11]
	v_mov_b32_e32 v12, v109
	v_mov_b32_e32 v13, v108
	v_mul_f32_e32 v2, v11, v108
	v_pk_fma_f32 v[48:49], v[10:11], v[12:13], v[2:3] op_sel_hi:[1,1,0] neg_lo:[0,0,1] neg_hi:[0,0,1]
	v_mul_f32_e32 v2, v11, v109
	v_pk_fma_f32 v[50:51], v[10:11], v[108:109], v[2:3] op_sel_hi:[1,1,0]
	v_pk_mul_f32 v[10:11], v[0:1], v[156:157] op_sel_hi:[0,1]
	v_mov_b32_e32 v6, v3
	v_pk_mul_f32 v[2:3], v[6:7], v[10:11]
	v_mov_b32_e32 v152, v4
	v_mul_f32_e32 v4, v3, v101
	v_pk_fma_f32 v[52:53], v[2:3], v[100:101], v[4:5] op_sel_hi:[1,1,0] neg_lo:[0,0,1] neg_hi:[0,0,1]
	v_mov_b32_e32 v6, v101
	v_mov_b32_e32 v7, v100
	v_mul_f32_e32 v4, v3, v100
	v_mov_b32_e32 v153, v8
	v_pk_fma_f32 v[54:55], v[2:3], v[6:7], v[4:5] op_sel_hi:[1,1,0]
	v_pk_mul_f32 v[2:3], v[0:1], v[56:57] op_sel_hi:[0,1]
	v_pk_mul_f32 v[2:3], v[152:153], v[2:3]
	v_mov_b32_e32 v6, v111
	v_mov_b32_e32 v7, v110
	v_mul_f32_e32 v4, v3, v110
	v_pk_fma_f32 v[56:57], v[2:3], v[6:7], v[4:5] op_sel_hi:[1,1,0] neg_lo:[0,0,1] neg_hi:[0,0,1]
	v_mul_f32_e32 v4, v3, v111
	v_pk_fma_f32 v[58:59], v[2:3], v[110:111], v[4:5] op_sel_hi:[1,1,0]
	v_pk_mul_f32 v[2:3], v[0:1], v[154:155] op_sel_hi:[0,1]
	v_mov_b32_e32 v8, v5
	v_pk_mul_f32 v[2:3], v[8:9], v[2:3]
	v_cvt_pk_bf16_f32 v152, v36, v32
	v_cvt_pk_bf16_f32 v153, v42, v34
	v_cvt_pk_bf16_f32 v154, v48, v52
	v_add_u32_e32 v96, 17, v78
	v_mul_f32_e32 v4, v3, v99
	v_pk_fma_f32 v[64:65], v[2:3], v[98:99], v[4:5] op_sel_hi:[1,1,0] neg_lo:[0,0,1] neg_hi:[0,0,1]
	v_mov_b32_e32 v4, v99
	v_mov_b32_e32 v5, v98
	v_mul_f32_e32 v6, v3, v98
	v_pk_fma_f32 v[82:83], v[2:3], v[4:5], v[6:7] op_sel_hi:[1,1,0]
	v_cvt_pk_bf16_f32 v155, v56, v64
	v_cvt_pk_bf16_f32 v148, v38, v40
	v_cvt_pk_bf16_f32 v149, v44, v46
	v_cvt_pk_bf16_f32 v150, v50, v54
	v_cvt_f32_i32_e32 v96, v96
	v_cvt_pk_bf16_f32 v151, v58, v82
	global_load_dwordx4 v[2:5], v[14:15], off offset:80
	global_load_dwordx4 v[6:9], v[14:15], off offset:64
	global_load_dwordx4 v[10:13], v[14:15], off offset:192
	global_load_dwordx4 v[128:131], v[14:15], off offset:208
	v_mul_f32_e32 v176, 0.15915494, v79
	v_mul_f32_e32 v96, 0xbed49a78, v96
	v_exp_f32_e32 v98, v96
	v_mul_f32_e32 v79, v176, v145
	v_floor_f32_e32 v79, v79
	v_fma_f32 v79, v176, v145, -v79
	v_mul_f32_e32 v177, 0.15915494, v98
	v_add_u32_e32 v98, 18, v78
	v_cvt_f32_i32_e32 v98, v98
	v_sin_f32_e32 v96, v79
	v_cos_f32_e32 v97, v79
	v_mul_f32_e32 v79, v177, v145
	v_floor_f32_e32 v79, v79
	v_fma_f32 v79, v177, v145, -v79
	v_mul_f32_e32 v98, 0xbed49a78, v98
	v_sin_f32_e32 v99, v79
	v_exp_f32_e32 v100, v98
	v_cos_f32_e32 v98, v79
	v_add_u32_e32 v79, 19, v78
	v_cvt_f32_i32_e32 v79, v79
	v_add_u32_e32 v104, 20, v78
	v_cvt_f32_i32_e32 v104, v104
	v_mul_f32_e32 v178, 0.15915494, v100
	v_mul_f32_e32 v79, 0xbed49a78, v79
	v_exp_f32_e32 v79, v79
	v_mul_f32_e32 v104, 0xbed49a78, v104
	v_exp_f32_e32 v104, v104
	v_mul_f32_e32 v100, v178, v145
	v_mul_f32_e32 v179, 0.15915494, v79
	v_mul_f32_e32 v79, v179, v145
	v_floor_f32_e32 v79, v79
	v_fma_f32 v79, v179, v145, -v79
	v_mul_f32_e32 v180, 0.15915494, v104
	v_sin_f32_e32 v107, v79
	v_cos_f32_e32 v106, v79
	v_add_u32_e32 v79, 21, v78
	v_mul_f32_e32 v104, v180, v145
	v_cvt_f32_i32_e32 v79, v79
	v_floor_f32_e32 v104, v104
	v_fma_f32 v104, v180, v145, -v104
	v_sin_f32_e32 v110, v104
	v_cos_f32_e32 v111, v104
	v_add_u32_e32 v104, 22, v78
	v_add_u32_e32 v78, 23, v78
	v_cvt_f32_i32_e32 v104, v104
	v_cvt_f32_i32_e32 v78, v78
	v_mul_f32_e32 v79, 0xbed49a78, v79
	v_exp_f32_e32 v79, v79
	v_mul_f32_e32 v104, 0xbed49a78, v104
	v_mul_f32_e32 v78, 0xbed49a78, v78
	v_exp_f32_e32 v104, v104
	v_exp_f32_e32 v78, v78
	v_mul_f32_e32 v181, 0.15915494, v79
	v_mul_f32_e32 v79, v181, v145
	v_floor_f32_e32 v79, v79
	v_fma_f32 v79, v181, v145, -v79
	v_mul_f32_e32 v182, 0.15915494, v104
	v_mul_f32_e32 v183, 0.15915494, v78
	v_sin_f32_e32 v133, v79
	v_cos_f32_e32 v132, v79
	v_mul_f32_e32 v79, v182, v145
	v_mul_f32_e32 v78, v183, v145
	v_floor_f32_e32 v79, v79
	v_floor_f32_e32 v78, v78
	v_fma_f32 v79, v182, v145, -v79
	v_fma_f32 v78, v183, v145, -v78
	v_sin_f32_e32 v134, v79
	v_cos_f32_e32 v135, v79
	v_sin_f32_e32 v147, v78
	v_cos_f32_e32 v146, v78
	v_pk_mul_f32 v[78:79], v[0:1], v[124:125] op_sel_hi:[0,1]
	v_floor_f32_e32 v100, v100
	v_fma_f32 v101, v178, v145, -v100
	v_sin_f32_e32 v100, v101
	v_cos_f32_e32 v101, v101
	v_pk_mul_f32 v[102:103], v[0:1], v[102:103] op_sel_hi:[0,1]
	v_pk_mul_f32 v[94:95], v[0:1], v[94:95] op_sel_hi:[0,1]
	s_waitcnt vmcnt(2)
; __device__ __forceinline__ unsigned cvtpk(float lo, float hi) { unsigned r; asm volatile("v_cvt_pk_bf16_f32 %0, %1, %2" : "=v"(r) : "v"(lo), "v"(hi)); return r; }
; __device__ __forceinline__ float bflo(unsigned w) { return __uint_as_float(w << 16); }
; __device__ __forceinline__ float bfhi(unsigned w) { return __uint_as_float(w & 0xffff0000u); }
; __device__ __forceinline__ float sin_rev(float rev) { return __builtin_amdgcn_sinf(rev); }
; __device__ __forceinline__ float cos_rev(float rev) { return __builtin_amdgcn_cosf(rev); }
; __device__ __forceinline__ void attn_item(const bf16_t* __restrict__ Qb, const bf16_t* __restrict__ Kh, const bf16_t* __restrict__ Vh, const bf16_t* __restrict__ Zb, ...
;     ...
;     for (int bb = 0; bb < 4; ++bb) { const int d1 = (bb & 1) + 4 * (bb >> 1), d2 = d1 + 2;
;       const float pos = (bb < 2) ? prow : pcol; const float* g1p = qg + d1 * 16 + hq * 8; const float* g2p = qg + d2 * 16 + hq * 8;
;       const f32x4 g1a = *(const f32x4*)g1p, g1b = *(const f32x4*)(g1p + 4), g2a = *(const f32x4*)g2p, g2b = *(const f32x4*)(g2p + 4);
;       float o1[8], o2[8];
; #pragma unroll
;       for (int e = 0; e < 8; ++e) { const unsigned w1 = (e < 2) ? qw[d1].x : (e < 4) ? qw[d1].y : (e < 6) ? qw[d1].z : qw[d1].w, w2 = (e < 2) ? qw[d2].x : (e < 4) ? qw[d2].y : (e < 6) ? qw[d2].z : qw[d2].w;
;         const float x1 = (e & 1) ? bfhi(w1) : bflo(w1), x2 = (e & 1) ? bfhi(w2) : bflo(w2); const float ga = (e < 4) ? g1a[e & 3] : g1b[e & 3], gb = (e < 4) ? g2a[e & 3] : g2b[e & 3];
;         const int fi = (d1 & 1) * 16 + hq * 8 + e; float rev = pos * (__builtin_amdgcn_exp2f(-(float)fi * (13.287712379549449f / 32.0f)) * 0.15915494309189535f); rev -= floorf(rev);
;         const float sn = sin_rev(rev), cs = cos_rev(rev), y1 = x1 * rstd * ga, y2 = x2 * rstd * gb; o1[e] = y1 * cs - y2 * sn; o2[e] = y2 * cs + y1 * sn; }
; #pragma unroll
;       for (int e = 0; e < 8; ++e) qn2 += o1[e] * o1[e] + o2[e] * o2[e];
;       u32x4 p1 = {cvtpk(o1[0], o1[1]), cvtpk(o1[2], o1[3]), cvtpk(o1[4], o1[5]), cvtpk(o1[6], o1[7])}, p2 = {cvtpk(o2[0], o2[1]), cvtpk(o2[2], o2[3]), cvtpk(o2[4], o2[5]), cvtpk(o2[6], o2[7])};
;       qr[d1] = *reinterpret_cast<bf16x8*>(&p1); qr[d2] = *reinterpret_cast<bf16x8*>(&p2); }
	v_mov_b32_e32 v104, v6
	s_waitcnt vmcnt(1)
	v_mov_b32_e32 v105, v10
	v_pk_mul_f32 v[104:105], v[78:79], v[104:105]
	v_mov_b32_e32 v78, v97
	v_mov_b32_e32 v79, v96
	v_mul_f32_e32 v6, v96, v105
	v_pk_fma_f32 v[78:79], v[78:79], v[104:105], v[6:7] op_sel_hi:[1,1,0] neg_lo:[0,0,1] neg_hi:[0,0,1]
	v_mul_f32_e32 v6, v97, v105
	v_pk_fma_f32 v[96:97], v[96:97], v[104:105], v[6:7] op_sel_hi:[1,1,0]
	v_pk_mul_f32 v[104:105], v[0:1], v[116:117] op_sel_hi:[0,1]
	v_mov_b32_e32 v10, v7
	v_pk_mul_f32 v[6:7], v[104:105], v[10:11]
	v_pk_mul_f32 v[76:77], v[0:1], v[76:77] op_sel_hi:[0,1]
	v_mul_f32_e32 v10, v99, v7
	v_pk_fma_f32 v[104:105], v[98:99], v[6:7], v[10:11] op_sel_hi:[1,1,0] neg_lo:[0,0,1] neg_hi:[0,0,1]
	v_mov_b32_e32 v10, v99
	v_mov_b32_e32 v11, v98
	v_mul_f32_e32 v98, v98, v7
	v_pk_fma_f32 v[108:109], v[10:11], v[6:7], v[98:99] op_sel_hi:[1,1,0]
	v_pk_mul_f32 v[6:7], v[0:1], v[112:113] op_sel_hi:[0,1]
	v_mov_b32_e32 v10, v8
	v_mov_b32_e32 v11, v12
	v_pk_mul_f32 v[6:7], v[6:7], v[10:11]
	v_mov_b32_e32 v10, v101
	v_mov_b32_e32 v11, v100
	v_mul_f32_e32 v8, v100, v7
	v_pk_fma_f32 v[112:113], v[10:11], v[6:7], v[8:9] op_sel_hi:[1,1,0] neg_lo:[0,0,1] neg_hi:[0,0,1]
	v_mul_f32_e32 v8, v101, v7
	v_pk_fma_f32 v[116:117], v[100:101], v[6:7], v[8:9] op_sel_hi:[1,1,0]
	v_pk_mul_f32 v[6:7], v[0:1], v[122:123] op_sel_hi:[0,1]
	v_mov_b32_e32 v12, v9
	v_pk_mul_f32 v[6:7], v[6:7], v[12:13]
	v_cvt_pk_bf16_f32 v160, v78, v104
	s_mulk_i32 s0, 0x2080
	v_mul_f32_e32 v8, v107, v7
	v_pk_fma_f32 v[122:123], v[106:107], v[6:7], v[8:9] op_sel_hi:[1,1,0] neg_lo:[0,0,1] neg_hi:[0,0,1]
	v_mov_b32_e32 v8, v107
	v_mov_b32_e32 v9, v106
	v_mul_f32_e32 v10, v106, v7
	v_pk_fma_f32 v[124:125], v[8:9], v[6:7], v[10:11] op_sel_hi:[1,1,0]
	v_pk_mul_f32 v[6:7], v[0:1], v[126:127] op_sel_hi:[0,1]
	v_mov_b32_e32 v8, v2
	s_waitcnt vmcnt(0)
	v_mov_b32_e32 v9, v128
	v_pk_mul_f32 v[6:7], v[6:7], v[8:9]
	v_mov_b32_e32 v8, v111
	v_mov_b32_e32 v9, v110
	v_mul_f32_e32 v2, v110, v7
	v_pk_fma_f32 v[98:99], v[8:9], v[6:7], v[2:3] op_sel_hi:[1,1,0] neg_lo:[0,0,1] neg_hi:[0,0,1]
	v_mul_f32_e32 v2, v111, v7
	v_pk_fma_f32 v[100:101], v[110:111], v[6:7], v[2:3] op_sel_hi:[1,1,0]
	v_pk_mul_f32 v[6:7], v[0:1], v[120:121] op_sel_hi:[0,1]
	v_mov_b32_e32 v128, v3
	v_pk_mul_f32 v[2:3], v[6:7], v[128:129]
	v_cvt_pk_bf16_f32 v161, v112, v122
	v_and_b32_e32 v128, 63, v136
	v_mul_f32_e32 v6, v133, v3
	v_pk_fma_f32 v[106:107], v[132:133], v[2:3], v[6:7] op_sel_hi:[1,1,0] neg_lo:[0,0,1] neg_hi:[0,0,1]
	v_mov_b32_e32 v6, v133
	v_mov_b32_e32 v7, v132
	v_mul_f32_e32 v8, v132, v3
	v_pk_fma_f32 v[110:111], v[6:7], v[2:3], v[8:9] op_sel_hi:[1,1,0]
	v_pk_mul_f32 v[2:3], v[0:1], v[114:115] op_sel_hi:[0,1]
	v_mov_b32_e32 v6, v4
	v_mov_b32_e32 v7, v130
	v_pk_mul_f32 v[2:3], v[2:3], v[6:7]
	v_mov_b32_e32 v6, v135
	v_mov_b32_e32 v7, v134
	v_mul_f32_e32 v4, v134, v3
	v_pk_fma_f32 v[114:115], v[6:7], v[2:3], v[4:5] op_sel_hi:[1,1,0] neg_lo:[0,0,1] neg_hi:[0,0,1]
	v_mul_f32_e32 v4, v135, v3
	v_pk_fma_f32 v[120:121], v[134:135], v[2:3], v[4:5] op_sel_hi:[1,1,0]
	v_pk_mul_f32 v[2:3], v[0:1], v[118:119] op_sel_hi:[0,1]
	v_mov_b32_e32 v130, v5
	v_pk_mul_f32 v[2:3], v[2:3], v[130:131]
	v_cvt_pk_bf16_f32 v162, v98, v106
	v_cvt_f32_ubyte0_e32 v189, v128
	v_mul_f32_e32 v4, v147, v3
	v_pk_fma_f32 v[118:119], v[146:147], v[2:3], v[4:5] op_sel_hi:[1,1,0] neg_lo:[0,0,1] neg_hi:[0,0,1]
	v_mov_b32_e32 v4, v147
	v_mov_b32_e32 v5, v146
	v_mul_f32_e32 v6, v146, v3
	v_pk_fma_f32 v[126:127], v[4:5], v[2:3], v[6:7] op_sel_hi:[1,1,0]
	v_cvt_pk_bf16_f32 v163, v114, v118
	v_cvt_pk_bf16_f32 v156, v96, v108
	v_cvt_pk_bf16_f32 v157, v116, v124
	v_cvt_pk_bf16_f32 v158, v100, v110
	v_mul_f32_e32 v130, v138, v189
	v_cvt_pk_bf16_f32 v159, v120, v126
	global_load_dwordx4 v[2:5], v[14:15], off offset:256
	global_load_dwordx4 v[6:9], v[14:15], off offset:384
	global_load_dwordx4 v[10:13], v[14:15], off offset:272
	global_load_dwordx4 v[164:167], v[14:15], off offset:400
	v_mul_f32_e32 v128, v137, v189
	v_floor_f32_e32 v130, v130
	v_floor_f32_e32 v128, v128
	v_fma_f32 v130, v138, v189, -v130
	v_mul_f32_e32 v138, v142, v189
	v_fma_f32 v129, v137, v189, -v128
	v_floor_f32_e32 v138, v138
	v_sin_f32_e32 v128, v129
	v_cos_f32_e32 v129, v129
	v_fma_f32 v138, v142, v189, -v138
	v_mul_f32_e32 v142, v144, v189
	v_floor_f32_e32 v142, v142
	v_fma_f32 v142, v144, v189, -v142
	v_sin_f32_e32 v131, v130
	v_cos_f32_e32 v130, v130
	v_mul_f32_e32 v132, v139, v189
	v_floor_f32_e32 v132, v132
	v_fma_f32 v133, v139, v189, -v132
	v_sin_f32_e32 v132, v133
	v_cos_f32_e32 v133, v133
	v_mul_f32_e32 v134, v140, v189
	v_floor_f32_e32 v134, v134
	v_fma_f32 v134, v140, v189, -v134
	v_sin_f32_e32 v135, v134
	v_cos_f32_e32 v134, v134
	v_mul_f32_e32 v136, v141, v189
	v_floor_f32_e32 v136, v136
	v_fma_f32 v137, v141, v189, -v136
	v_sin_f32_e32 v136, v137
	v_cos_f32_e32 v137, v137
	v_sin_f32_e32 v139, v138
	v_cos_f32_e32 v138, v138
	v_mul_f32_e32 v140, v143, v189
	v_floor_f32_e32 v140, v140
	v_fma_f32 v141, v143, v189, -v140
	v_sin_f32_e32 v140, v141
	v_cos_f32_e32 v141, v141
	v_sin_f32_e32 v143, v142
	v_cos_f32_e32 v142, v142
	s_add_u32 s0, s42, s0
	s_addc_u32 s1, s43, 0
	v_lshlrev_b32_e32 v206, 3, v186
	s_add_u32 s0, s0, s8
	s_addc_u32 s1, s1, 0
	v_pk_mul_f32 v[38:39], v[38:39], v[38:39]
	v_lshlrev_b32_e32 v221, 8, v187
	v_pk_fma_f32 v[36:37], v[36:37], v[36:37], v[38:39]
	v_pk_mul_f32 v[38:39], v[40:41], v[40:41]
	v_and_b32_e32 v208, 63, v186
	v_pk_fma_f32 v[32:33], v[32:33], v[32:33], v[38:39]
	v_and_b32_e32 v39, 24, v206
	v_pk_add_f32 v[32:33], v[36:37], v[32:33]
	v_pk_mul_f32 v[36:37], v[44:45], v[44:45]
	s_cmp_lg_u32 0, -1
	v_pk_fma_f32 v[36:37], v[42:43], v[42:43], v[36:37]
	s_mul_i32 s9, s6, 0x8200000
	v_pk_add_f32 v[32:33], v[36:37], v[32:33]
	v_pk_mul_f32 v[36:37], v[46:47], v[46:47]
	s_cselect_b32 s6, 0, 0
	v_pk_fma_f32 v[34:35], v[34:35], v[34:35], v[36:37]
	v_lshrrev_b32_e32 v36, 5, v186
	v_pk_add_f32 v[32:33], v[34:35], v[32:33]
	v_pk_mul_f32 v[34:35], v[50:51], v[50:51]
	v_bfe_u32 v37, v206, 5, 2
	v_pk_fma_f32 v[34:35], v[48:49], v[48:49], v[34:35]
	v_and_or_b32 v36, v36, s58, v37
	v_pk_add_f32 v[32:33], v[34:35], v[32:33]
	v_pk_mul_f32 v[34:35], v[54:55], v[54:55]
	v_mov_b32_e32 v244, 1.0
	v_pk_fma_f32 v[34:35], v[52:53], v[52:53], v[34:35]
	s_mov_b32 s76, 0x10000
	v_pk_add_f32 v[32:33], v[34:35], v[32:33]
	v_pk_mul_f32 v[34:35], v[58:59], v[58:59]
	v_pk_mul_f32 v[58:59], v[120:121], v[120:121]
	v_pk_fma_f32 v[34:35], v[56:57], v[56:57], v[34:35]
	s_mov_b32 s77, 0x8000
	s_waitcnt vmcnt(3)
; __device__ __forceinline__ unsigned cvtpk(float lo, float hi) { unsigned r; asm volatile("v_cvt_pk_bf16_f32 %0, %1, %2" : "=v"(r) : "v"(lo), "v"(hi)); return r; }
; __device__ __forceinline__ float bflo(unsigned w) { return __uint_as_float(w << 16); }
; __device__ __forceinline__ float bfhi(unsigned w) { return __uint_as_float(w & 0xffff0000u); }
; __device__ __forceinline__ float sin_rev(float rev) { return __builtin_amdgcn_sinf(rev); }
; __device__ __forceinline__ float cos_rev(float rev) { return __builtin_amdgcn_cosf(rev); }
; __device__ __forceinline__ void attn_item(const bf16_t* __restrict__ Qb, const bf16_t* __restrict__ Kh, const bf16_t* __restrict__ Vh, const bf16_t* __restrict__ Zb, ...
;     ...
;     for (int bb = 0; bb < 4; ++bb) { const int d1 = (bb & 1) + 4 * (bb >> 1), d2 = d1 + 2;
;       const float pos = (bb < 2) ? prow : pcol; const float* g1p = qg + d1 * 16 + hq * 8; const float* g2p = qg + d2 * 16 + hq * 8;
;       const f32x4 g1a = *(const f32x4*)g1p, g1b = *(const f32x4*)(g1p + 4), g2a = *(const f32x4*)g2p, g2b = *(const f32x4*)(g2p + 4);
;       float o1[8], o2[8];
; #pragma unroll
;       for (int e = 0; e < 8; ++e) { const unsigned w1 = (e < 2) ? qw[d1].x : (e < 4) ? qw[d1].y : (e < 6) ? qw[d1].z : qw[d1].w, w2 = (e < 2) ? qw[d2].x : (e < 4) ? qw[d2].y : (e < 6) ? qw[d2].z : qw[d2].w;
;         const float x1 = (e & 1) ? bfhi(w1) : bflo(w1), x2 = (e & 1) ? bfhi(w2) : bflo(w2); const float ga = (e < 4) ? g1a[e & 3] : g1b[e & 3], gb = (e < 4) ? g2a[e & 3] : g2b[e & 3];
;         const int fi = (d1 & 1) * 16 + hq * 8 + e; float rev = pos * (__builtin_amdgcn_exp2f(-(float)fi * (13.287712379549449f / 32.0f)) * 0.15915494309189535f); rev -= floorf(rev);
;         const float sn = sin_rev(rev), cs = cos_rev(rev), y1 = x1 * rstd * ga, y2 = x2 * rstd * gb; o1[e] = y1 * cs - y2 * sn; o2[e] = y2 * cs + y1 * sn; }
; #pragma unroll
;       for (int e = 0; e < 8; ++e) qn2 += o1[e] * o1[e] + o2[e] * o2[e];
;       u32x4 p1 = {cvtpk(o1[0], o1[1]), cvtpk(o1[2], o1[3]), cvtpk(o1[4], o1[5]), cvtpk(o1[6], o1[7])}, p2 = {cvtpk(o2[0], o2[1]), cvtpk(o2[2], o2[3]), cvtpk(o2[4], o2[5]), cvtpk(o2[6], o2[7])};
;       qr[d1] = *reinterpret_cast<bf16x8*>(&p1); qr[d2] = *reinterpret_cast<bf16x8*>(&p2); }
	v_mov_b32_e32 v144, v2
	s_waitcnt vmcnt(2)
	v_mov_b32_e32 v145, v6
	v_pk_mul_f32 v[144:145], v[102:103], v[144:145]
	v_mov_b32_e32 v102, v129
	v_mov_b32_e32 v103, v128
	v_mul_f32_e32 v2, v128, v145
	v_pk_fma_f32 v[102:103], v[102:103], v[144:145], v[2:3] op_sel_hi:[1,1,0] neg_lo:[0,0,1] neg_hi:[0,0,1]
	v_mul_f32_e32 v2, v129, v145
	v_mov_b32_e32 v6, v3
	v_pk_fma_f32 v[128:129], v[128:129], v[144:145], v[2:3] op_sel_hi:[1,1,0]
	v_pk_mul_f32 v[2:3], v[94:95], v[6:7]
	v_mul_f32_e32 v144, v177, v189
	v_mul_f32_e32 v6, v131, v3
	v_pk_fma_f32 v[94:95], v[130:131], v[2:3], v[6:7] op_sel_hi:[1,1,0] neg_lo:[0,0,1] neg_hi:[0,0,1]
	v_mov_b32_e32 v6, v131
	v_mov_b32_e32 v7, v130
	v_mul_f32_e32 v130, v130, v3
	v_pk_fma_f32 v[130:131], v[6:7], v[2:3], v[130:131] op_sel_hi:[1,1,0]
	v_pk_mul_f32 v[2:3], v[0:1], v[92:93] op_sel_hi:[0,1]
	v_mov_b32_e32 v6, v4
	v_mov_b32_e32 v7, v8
	v_pk_mul_f32 v[2:3], v[2:3], v[6:7]
	v_mov_b32_e32 v6, v133
	v_mov_b32_e32 v7, v132
	v_mul_f32_e32 v4, v132, v3
	v_pk_fma_f32 v[92:93], v[6:7], v[2:3], v[4:5] op_sel_hi:[1,1,0] neg_lo:[0,0,1] neg_hi:[0,0,1]
	v_mul_f32_e32 v4, v133, v3
	v_pk_fma_f32 v[132:133], v[132:133], v[2:3], v[4:5] op_sel_hi:[1,1,0]
	v_pk_mul_f32 v[2:3], v[0:1], v[90:91] op_sel_hi:[0,1]
	v_mov_b32_e32 v8, v5
	v_pk_mul_f32 v[2:3], v[2:3], v[8:9]
	v_cvt_pk_bf16_f32 v168, v102, v94
	v_floor_f32_e32 v144, v144
	v_mul_f32_e32 v4, v135, v3
	v_pk_fma_f32 v[90:91], v[134:135], v[2:3], v[4:5] op_sel_hi:[1,1,0] neg_lo:[0,0,1] neg_hi:[0,0,1]
	v_mov_b32_e32 v4, v135
	v_mov_b32_e32 v5, v134
	v_mul_f32_e32 v6, v134, v3
	v_pk_fma_f32 v[134:135], v[4:5], v[2:3], v[6:7] op_sel_hi:[1,1,0]
	v_pk_mul_f32 v[2:3], v[0:1], v[88:89] op_sel_hi:[0,1]
	s_waitcnt vmcnt(1)
	v_mov_b32_e32 v4, v10
	s_waitcnt vmcnt(0)
	v_mov_b32_e32 v5, v164
	v_pk_mul_f32 v[2:3], v[2:3], v[4:5]
	v_mov_b32_e32 v4, v137
	v_mov_b32_e32 v5, v136
	v_mul_f32_e32 v6, v136, v3
	v_pk_fma_f32 v[88:89], v[4:5], v[2:3], v[6:7] op_sel_hi:[1,1,0] neg_lo:[0,0,1] neg_hi:[0,0,1]
	v_mul_f32_e32 v4, v137, v3
	v_pk_fma_f32 v[136:137], v[136:137], v[2:3], v[4:5] op_sel_hi:[1,1,0]
	v_pk_mul_f32 v[2:3], v[0:1], v[86:87] op_sel_hi:[0,1]
	v_mov_b32_e32 v164, v11
	v_pk_mul_f32 v[2:3], v[2:3], v[164:165]
	v_cvt_pk_bf16_f32 v169, v92, v90
	v_fma_f32 v144, v177, v189, -v144
	v_mul_f32_e32 v4, v139, v3
	v_pk_fma_f32 v[86:87], v[138:139], v[2:3], v[4:5] op_sel_hi:[1,1,0] neg_lo:[0,0,1] neg_hi:[0,0,1]
	v_mov_b32_e32 v4, v139
	v_mov_b32_e32 v5, v138
	v_mul_f32_e32 v6, v138, v3
	v_pk_fma_f32 v[138:139], v[4:5], v[2:3], v[6:7] op_sel_hi:[1,1,0]
	v_pk_mul_f32 v[2:3], v[0:1], v[84:85] op_sel_hi:[0,1]
	v_mov_b32_e32 v4, v12
	v_mov_b32_e32 v5, v166
	v_pk_mul_f32 v[2:3], v[2:3], v[4:5]
	v_mov_b32_e32 v4, v141
	v_mov_b32_e32 v5, v140
	v_mul_f32_e32 v6, v140, v3
	v_pk_fma_f32 v[84:85], v[4:5], v[2:3], v[6:7] op_sel_hi:[1,1,0] neg_lo:[0,0,1] neg_hi:[0,0,1]
	v_mul_f32_e32 v4, v141, v3
	v_pk_fma_f32 v[140:141], v[140:141], v[2:3], v[4:5] op_sel_hi:[1,1,0]
	v_pk_mul_f32 v[2:3], v[0:1], v[80:81] op_sel_hi:[0,1]
	v_mov_b32_e32 v166, v13
	v_pk_mul_f32 v[2:3], v[2:3], v[166:167]
	v_cvt_pk_bf16_f32 v170, v88, v86
	v_sin_f32_e32 v147, v144
	v_mul_f32_e32 v4, v143, v3
	v_pk_fma_f32 v[80:81], v[142:143], v[2:3], v[4:5] op_sel_hi:[1,1,0] neg_lo:[0,0,1] neg_hi:[0,0,1]
	v_mov_b32_e32 v4, v143
	v_mov_b32_e32 v5, v142
	v_mul_f32_e32 v6, v142, v3
	v_pk_fma_f32 v[142:143], v[4:5], v[2:3], v[6:7] op_sel_hi:[1,1,0]
	v_cvt_pk_bf16_f32 v171, v84, v80
	v_cvt_pk_bf16_f32 v164, v128, v130
	v_cvt_pk_bf16_f32 v165, v132, v134
	v_cvt_pk_bf16_f32 v166, v136, v138
	v_cos_f32_e32 v146, v144
	v_cvt_pk_bf16_f32 v167, v140, v142
	global_load_dwordx4 v[2:5], v[14:15], off offset:320
	global_load_dwordx4 v[6:9], v[14:15], off offset:448
	global_load_dwordx4 v[10:13], v[14:15], off offset:336
	global_load_dwordx4 v[172:175], v[14:15], off offset:464
	v_mul_f32_e32 v144, v178, v189
	v_mul_f32_e32 v14, v176, v189
	v_floor_f32_e32 v144, v144
	v_floor_f32_e32 v14, v14
	v_fma_f32 v144, v178, v189, -v144
	v_fma_f32 v15, v176, v189, -v14
	v_sin_f32_e32 v176, v144
	v_cos_f32_e32 v177, v144
	v_mul_f32_e32 v144, v179, v189
	v_floor_f32_e32 v144, v144
	v_fma_f32 v144, v179, v189, -v144
	v_sin_f32_e32 v179, v144
	v_cos_f32_e32 v178, v144
	v_mul_f32_e32 v144, v180, v189
	v_floor_f32_e32 v144, v144
	v_fma_f32 v144, v180, v189, -v144
	v_sin_f32_e32 v184, v144
	v_cos_f32_e32 v185, v144
	v_mul_f32_e32 v144, v181, v189
	v_floor_f32_e32 v144, v144
	v_fma_f32 v144, v181, v189, -v144
	v_sin_f32_e32 v191, v144
	v_cos_f32_e32 v190, v144
	v_mul_f32_e32 v144, v182, v189
	v_floor_f32_e32 v144, v144
	v_fma_f32 v144, v182, v189, -v144
	v_sin_f32_e32 v192, v144
	v_cos_f32_e32 v193, v144
	v_mul_f32_e32 v144, v183, v189
	v_sin_f32_e32 v14, v15
	v_cos_f32_e32 v15, v15
	v_floor_f32_e32 v144, v144
	v_fma_f32 v144, v183, v189, -v144
	v_sin_f32_e32 v195, v144
	v_cos_f32_e32 v194, v144
	v_ashrrev_i32_e32 v189, 4, v186
	v_add_u32_e32 v207, 32, v189
	v_pk_add_f32 v[32:33], v[34:35], v[32:33]
	v_pk_mul_f32 v[34:35], v[82:83], v[82:83]
	v_lshlrev_b32_e32 v38, 5, v189
	v_pk_fma_f32 v[34:35], v[64:65], v[64:65], v[34:35]
	v_and_or_b32 v38, v38, s59, v39
	v_pk_add_f32 v[32:33], v[34:35], v[32:33]
	v_pk_mul_f32 v[34:35], v[96:97], v[96:97]
	v_lshlrev_b32_e32 v38, 1, v38
	v_pk_fma_f32 v[34:35], v[78:79], v[78:79], v[34:35]
	v_lshl_or_b32 v228, v36, 9, v38
	v_pk_add_f32 v[32:33], v[34:35], v[32:33]
	v_pk_mul_f32 v[34:35], v[108:109], v[108:109]
	v_lshrrev_b32_e32 v36, 1, v207
	v_pk_fma_f32 v[34:35], v[104:105], v[104:105], v[34:35]
	v_and_or_b32 v36, v36, s58, v37
	v_lshlrev_b32_e32 v82, 4, v186
	v_add_u32_e32 v108, 0, v228
	v_pk_add_f32 v[32:33], v[34:35], v[32:33]
	v_pk_mul_f32 v[34:35], v[116:117], v[116:117]
	v_lshl_or_b32 v229, v36, 9, v38
	v_lshlrev_b32_e32 v36, 8, v189
	v_and_b32_e32 v38, 0xf0, v186
	v_lshlrev_b32_e32 v39, 8, v207
	v_pk_fma_f32 v[34:35], v[112:113], v[112:113], v[34:35]
	v_add_u32_e32 v83, 0, v221
	v_pk_add_f32 v[32:33], v[34:35], v[32:33]
	v_pk_mul_f32 v[34:35], v[124:125], v[124:125]
	v_add_u32_e32 v109, 0, v229
	v_pk_fma_f32 v[34:35], v[122:123], v[122:123], v[34:35]
	v_pk_mul_f32 v[78:79], v[126:127], v[126:127]
	v_pk_add_f32 v[32:33], v[34:35], v[32:33]
	v_pk_mul_f32 v[34:35], v[100:101], v[100:101]
	s_mov_b32 s78, -1
	v_pk_fma_f32 v[34:35], v[98:99], v[98:99], v[34:35]
	v_mov_b32_e32 v219, 0
	v_pk_add_f32 v[32:33], v[34:35], v[32:33]
	v_pk_mul_f32 v[34:35], v[110:111], v[110:111]
	s_waitcnt vmcnt(3)
; __device__ __forceinline__ unsigned cvtpk(float lo, float hi) { unsigned r; asm volatile("v_cvt_pk_bf16_f32 %0, %1, %2" : "=v"(r) : "v"(lo), "v"(hi)); return r; }
; __device__ __forceinline__ void attn_item(const bf16_t* __restrict__ Qb, const bf16_t* __restrict__ Kh, const bf16_t* __restrict__ Vh, const bf16_t* __restrict__ Zb, ...
;     ...
;     for (int bb = 0; bb < 4; ++bb) { const int d1 = (bb & 1) + 4 * (bb >> 1), d2 = d1 + 2;
;       const float pos = (bb < 2) ? prow : pcol; const float* g1p = qg + d1 * 16 + hq * 8; const float* g2p = qg + d2 * 16 + hq * 8;
;       const f32x4 g1a = *(const f32x4*)g1p, g1b = *(const f32x4*)(g1p + 4), g2a = *(const f32x4*)g2p, g2b = *(const f32x4*)(g2p + 4);
;       float o1[8], o2[8];
; #pragma unroll
;       for (int e = 0; e < 8; ++e) { const unsigned w1 = (e < 2) ? qw[d1].x : (e < 4) ? qw[d1].y : (e < 6) ? qw[d1].z : qw[d1].w, w2 = (e < 2) ? qw[d2].x : (e < 4) ? qw[d2].y : (e < 6) ? qw[d2].z : qw[d2].w;
;         const float x1 = (e & 1) ? bfhi(w1) : bflo(w1), x2 = (e & 1) ? bfhi(w2) : bflo(w2); const float ga = (e < 4) ? g1a[e & 3] : g1b[e & 3], gb = (e < 4) ? g2a[e & 3] : g2b[e & 3];
;         const int fi = (d1 & 1) * 16 + hq * 8 + e; float rev = pos * (__builtin_amdgcn_exp2f(-(float)fi * (13.287712379549449f / 32.0f)) * 0.15915494309189535f); rev -= floorf(rev);
;         const float sn = sin_rev(rev), cs = cos_rev(rev), y1 = x1 * rstd * ga, y2 = x2 * rstd * gb; o1[e] = y1 * cs - y2 * sn; o2[e] = y2 * cs + y1 * sn; }
; #pragma unroll
;       for (int e = 0; e < 8; ++e) qn2 += o1[e] * o1[e] + o2[e] * o2[e];
;       u32x4 p1 = {cvtpk(o1[0], o1[1]), cvtpk(o1[2], o1[3]), cvtpk(o1[4], o1[5]), cvtpk(o1[6], o1[7])}, p2 = {cvtpk(o2[0], o2[1]), cvtpk(o2[2], o2[3]), cvtpk(o2[4], o2[5]), cvtpk(o2[6], o2[7])};
;       qr[d1] = *reinterpret_cast<bf16x8*>(&p1); qr[d2] = *reinterpret_cast<bf16x8*>(&p2); }
;     ...
;   const int sr = tid >> 4, sc = (tid & 15) * 8, vst0 = v_st_nat(sr, sc), vst1 = v_st_nat(32 + sr, sc), kst0 = KOFF + KSWZ(sr, sc * 2), kst1 = KOFF + KSWZ(32 + sr, sc * 2);
;   const int vb0 = (int)(uintptr_t)lds + v_rd_base(lane);
;   struct { bf16x8 vs0, vs1, ks0, ks1; } sr_;
;     ...
;   f32x16 pA0, pA1, pB0, pB1; float alA, alB; VF8 vfa; bf16x8 pa0, pa1, pa2, pa3; const int NT = seq / KVBLK;
;   int s_prev = 0, s_cur = SLOT, s_next = 2 * SLOT;
;   SLOAD(0); SWAIT(); SWRITE(0); __syncthreads();
	v_mov_b32_e32 v144, v2
	s_waitcnt vmcnt(2)
	v_mov_b32_e32 v145, v6
	v_pk_mul_f32 v[144:145], v[76:77], v[144:145]
	v_mov_b32_e32 v76, v15
	v_mov_b32_e32 v77, v14
	v_mul_f32_e32 v2, v14, v145
	v_pk_fma_f32 v[76:77], v[76:77], v[144:145], v[2:3] op_sel_hi:[1,1,0] neg_lo:[0,0,1] neg_hi:[0,0,1]
	v_mul_f32_e32 v2, v15, v145
	v_pk_fma_f32 v[144:145], v[14:15], v[144:145], v[2:3] op_sel_hi:[1,1,0]
	v_pk_mul_f32 v[14:15], v[0:1], v[60:61] op_sel_hi:[0,1]
	v_mov_b32_e32 v6, v3
	v_pk_mul_f32 v[2:3], v[14:15], v[6:7]
	v_pk_fma_f32 v[34:35], v[106:107], v[106:107], v[34:35]
	v_mul_f32_e32 v6, v147, v3
	v_pk_fma_f32 v[60:61], v[146:147], v[2:3], v[6:7] op_sel_hi:[1,1,0] neg_lo:[0,0,1] neg_hi:[0,0,1]
	v_mov_b32_e32 v6, v147
	v_mov_b32_e32 v7, v146
	v_mul_f32_e32 v14, v146, v3
	v_pk_fma_f32 v[146:147], v[6:7], v[2:3], v[14:15] op_sel_hi:[1,1,0]
	v_pk_mul_f32 v[2:3], v[0:1], v[74:75] op_sel_hi:[0,1]
	v_mov_b32_e32 v6, v4
	v_mov_b32_e32 v7, v8
	v_pk_mul_f32 v[2:3], v[2:3], v[6:7]
	v_mov_b32_e32 v6, v177
	v_mov_b32_e32 v7, v176
	v_mul_f32_e32 v4, v176, v3
	v_pk_fma_f32 v[74:75], v[6:7], v[2:3], v[4:5] op_sel_hi:[1,1,0] neg_lo:[0,0,1] neg_hi:[0,0,1]
	v_mul_f32_e32 v4, v177, v3
	v_pk_fma_f32 v[180:181], v[176:177], v[2:3], v[4:5] op_sel_hi:[1,1,0]
	v_pk_mul_f32 v[2:3], v[0:1], v[66:67] op_sel_hi:[0,1]
	v_mov_b32_e32 v8, v5
	v_pk_mul_f32 v[2:3], v[2:3], v[8:9]
	s_waitcnt vmcnt(0)
	v_mov_b32_e32 v15, v174
	v_mul_f32_e32 v4, v179, v3
	v_pk_fma_f32 v[66:67], v[178:179], v[2:3], v[4:5] op_sel_hi:[1,1,0] neg_lo:[0,0,1] neg_hi:[0,0,1]
	v_mov_b32_e32 v4, v179
	v_mov_b32_e32 v5, v178
	v_mul_f32_e32 v6, v178, v3
	v_pk_fma_f32 v[182:183], v[4:5], v[2:3], v[6:7] op_sel_hi:[1,1,0]
	v_pk_mul_f32 v[2:3], v[0:1], v[72:73] op_sel_hi:[0,1]
	v_mov_b32_e32 v4, v10
	v_mov_b32_e32 v5, v172
	v_pk_mul_f32 v[6:7], v[0:1], v[62:63] op_sel_hi:[0,1]
	v_mov_b32_e32 v172, v11
	v_pk_mul_f32 v[2:3], v[2:3], v[4:5]
	v_mov_b32_e32 v4, v185
	v_mov_b32_e32 v5, v184
	v_pk_mul_f32 v[6:7], v[6:7], v[172:173]
	v_mov_b32_e32 v10, v191
	v_mov_b32_e32 v11, v190
	v_pk_mul_f32 v[62:63], v[0:1], v[70:71] op_sel_hi:[0,1]
	v_mov_b32_e32 v174, v13
	v_pk_mul_f32 v[4:5], v[4:5], v[2:3]
	v_pk_mul_f32 v[8:9], v[190:191], v[6:7]
	v_pk_mul_f32 v[6:7], v[10:11], v[6:7]
	v_pk_mul_f32 v[10:11], v[0:1], v[68:69] op_sel_hi:[0,1]
	v_mov_b32_e32 v14, v12
	v_pk_mul_f32 v[12:13], v[62:63], v[174:175]
	v_mov_b32_e32 v62, v195
	v_mov_b32_e32 v63, v194
	v_pk_mul_f32 v[2:3], v[184:185], v[2:3]
	v_pk_mul_f32 v[10:11], v[10:11], v[14:15]
	v_mov_b32_e32 v14, v193
	v_mov_b32_e32 v15, v192
	v_pk_mul_f32 v[68:69], v[194:195], v[12:13]
	v_pk_mul_f32 v[12:13], v[62:63], v[12:13]
	v_mov_b32_e32 v62, v8
	v_mov_b32_e32 v63, v4
	v_mov_b32_e32 v4, v9
	v_pk_mul_f32 v[14:15], v[14:15], v[10:11]
	v_pk_add_f32 v[62:63], v[62:63], v[4:5] neg_lo:[0,1] neg_hi:[0,1]
	v_mov_b32_e32 v4, v6
	v_mov_b32_e32 v5, v2
	v_mov_b32_e32 v2, v7
	v_pk_mul_f32 v[10:11], v[192:193], v[10:11]
	v_pk_add_f32 v[72:73], v[4:5], v[2:3]
	v_mov_b32_e32 v2, v68
	v_mov_b32_e32 v3, v14
	v_mov_b32_e32 v14, v69
	v_pk_add_f32 v[68:69], v[2:3], v[14:15] neg_lo:[0,1] neg_hi:[0,1]
	v_mov_b32_e32 v2, v12
	v_mov_b32_e32 v3, v10
	v_mov_b32_e32 v10, v13
	v_and_b32_e32 v70, 0x78, v206
	v_mov_b32_e32 v71, v1
	v_pk_add_f32 v[184:185], v[2:3], v[10:11]
	v_mad_i64_i32 v[2:3], s[36:37], v189, s61, v[70:71]
	v_lshl_add_u64 v[2:3], v[2:3], 1, s[0:1]
	v_cvt_pk_bf16_f32 v176, v76, v60
	v_cvt_pk_bf16_f32 v177, v74, v66
	v_cvt_pk_bf16_f32 v178, v63, v62
	v_cvt_pk_bf16_f32 v179, v69, v68
	v_cvt_pk_bf16_f32 v172, v144, v146
	v_cvt_pk_bf16_f32 v173, v180, v182
	v_cvt_pk_bf16_f32 v174, v73, v72
	v_cvt_pk_bf16_f32 v175, v185, v184
	global_load_dwordx4 v[190:193], v[2:3], off offset:2560
	v_mad_i64_i32 v[4:5], s[36:37], v207, s61, v[70:71]
	v_lshl_add_u64 v[4:5], v[4:5], 1, s[0:1]
	global_load_dwordx4 v[194:197], v[4:5], off offset:2560
	global_load_dwordx4 v[198:201], v[2:3], off offset:2048
	global_load_dwordx4 v[202:205], v[4:5], off offset:2048
	v_lshlrev_b32_e32 v37, 1, v70
	s_waitcnt vmcnt(0)
	v_bitop3_b32 v231, v37, v36, v38 bitop3:0xde
	v_bitop3_b32 v232, v39, v37, v38 bitop3:0xf6
	v_add_u32_e32 v112, 0, v231
	v_add_u32_e32 v113, 0, v232
	v_pk_add_f32 v[56:57], v[34:35], v[32:33]
	v_and_b32_e32 v0, 0x3fffffc0, v186
	v_mov_b32_e32 v14, v1
	v_mov_b32_e32 v15, v1
	v_lshl_add_u32 v213, v0, 2, s56
	v_mov_b32_e32 v0, v1
	v_mov_b32_e32 v2, v1
	v_mov_b32_e32 v3, v1
	v_mov_b32_e32 v4, v1
	v_mov_b32_e32 v5, v1
	v_mov_b32_e32 v6, v1
	v_mov_b32_e32 v7, v1
	v_mov_b32_e32 v8, v1
	v_mov_b32_e32 v9, v1
	v_mov_b32_e32 v10, v1
	v_mov_b32_e32 v11, v1
	v_mov_b32_e32 v12, v1
	v_mov_b32_e32 v13, v1
	v_or_b32_e32 v106, 0xc0, v212
	v_or_b32_e32 v107, 0xe0, v212
	v_lshl_add_u32 v220, v187, 2, v213
	s_waitcnt vmcnt(3)
	ds_write_b128 v108, v[190:193]
	v_and_b32_e32 v190, 0xf0, v82
	v_bitop3_b32 v234, v188, v190, 16 bitop3:0x6c
	v_add_u32_e32 v36, v83, v234
	s_waitcnt vmcnt(2)
	ds_write_b128 v109, v[194:197]
	s_waitcnt vmcnt(1)
	ds_write_b128 v112, v[198:201] offset:16384
	s_waitcnt vmcnt(0)
	ds_write_b128 v113, v[202:205] offset:16384
	s_waitcnt lgkmcnt(0)
	s_barrier
; #define SLOAD(k0) do { sr_.vs0 = *(const bf16x8*)(&Vh[(long)((k0) + sr) * LDK + sc]); sr_.vs1 = *(const bf16x8*)(&Vh[(long)((k0) + 32 + sr) * LDK + sc]); \
;     sr_.ks0 = *(const bf16x8*)(&Kh[(long)((k0) + sr) * LDK + sc]); sr_.ks1 = *(const bf16x8*)(&Kh[(long)((k0) + 32 + sr) * LDK + sc]); } while (0)
; __device__ __forceinline__ void qkt(f32x16& p0, f32x16& p1, const bf16_t* Ks, const bf16x8* qr, const f32x16& negm, int r32, int hi) {
; #pragma unroll
;   for (int d0 = 0; d0 < 8; ++d0) { int cb = (d0 * 16 + hi * 8) * 2;
;     bf16x8 b0 = *reinterpret_cast<const bf16x8*>((const char*)Ks + KSWZ(r32, cb));
;     bf16x8 b1 = *reinterpret_cast<const bf16x8*>((const char*)Ks + KSWZ(32 + r32, cb));
;     if (d0 == 0) { p0 = __builtin_amdgcn_mfma_f32_32x32x16_bf16(b0, qr[0], negm, 0, 0, 0); p1 = __builtin_amdgcn_mfma_f32_32x32x16_bf16(b1, qr[0], negm, 0, 0, 0); }
;     else { p0 = __builtin_amdgcn_mfma_f32_32x32x16_bf16(b0, qr[d0], p0, 0, 0, 0); p1 = __builtin_amdgcn_mfma_f32_32x32x16_bf16(b1, qr[d0], p1, 0, 0, 0); } }
; }
; __device__ __forceinline__ void attn_item(const bf16_t* __restrict__ Qb, const bf16_t* __restrict__ Kh, const bf16_t* __restrict__ Vh, const bf16_t* __restrict__ Zb, ...
;     ...
;   SLOAD(KVBLK);
;   qkt(pA0, pA1, (const bf16_t*)(lds + KOFF), qr, negm, r32, hi); partialSM<true>(pA0, pA1, m_reg, negm, alA);
	ds_read_b128 v[48:51], v36 offset:24576
	ds_read_b128 v[52:55], v36 offset:16384
	s_waitcnt lgkmcnt(0)
	v_mfma_f32_32x32x16_bf16 v[32:47], v[52:55], v[152:155], v[16:31]
	v_fma_f32 v52, v114, v114, v58
	v_fma_f32 v53, v115, v115, v59
	v_bitop3_b32 v233, v212, v190, 32 bitop3:0x36
	v_add_f32_e64 v64, v52, v56
	v_add_f32_e64 v65, v53, v57
	v_add_u32_e32 v56, v83, v233
	ds_read_b128 v[52:55], v56 offset:24576
	ds_read_b128 v[56:59], v56 offset:16384
	v_bitop3_b32 v230, v212, v190, 64 bitop3:0x36
	v_bitop3_b32 v227, v212, v190, s62 bitop3:0x36
	v_mfma_f32_32x32x16_bf16 v[16:31], v[48:51], v[152:155], v[16:31]
	v_fma_f32 v48, v118, v118, v78
	v_fma_f32 v49, v119, v119, v79
	v_mul_f32_e64 v50, v128, v128
	v_mul_f32_e64 v51, v129, v129
	v_add_f32_e64 v48, v48, v64
	v_add_f32_e64 v49, v49, v65
	v_pk_fma_f32 v[50:51], v[102:103], v[102:103], v[50:51]
	v_bitop3_b32 v226, v212, v190, s63 bitop3:0x36
	v_pk_add_f32 v[48:49], v[48:49], v[50:51]
	v_pk_mul_f32 v[50:51], v[130:131], v[130:131]
	s_waitcnt lgkmcnt(0)
	v_mfma_f32_32x32x16_bf16 v[32:47], v[56:59], v[160:163], v[32:47]
	v_fma_f32 v50, v94, v94, v50
	v_fma_f32 v51, v95, v95, v51
	v_add_u32_e32 v56, v83, v230
	v_add_f32_e64 v64, v50, v48
	v_add_f32_e64 v65, v51, v49
	v_pk_mul_f32 v[48:49], v[132:133], v[132:133]
	v_bitop3_b32 v225, v212, v190, s64 bitop3:0x36
	v_pk_fma_f32 v[78:79], v[92:93], v[92:93], v[48:49]
	ds_read_b128 v[48:51], v56 offset:24576
	ds_read_b128 v[56:59], v56 offset:16384
	v_mfma_f32_32x32x16_bf16 v[16:31], v[52:55], v[160:163], v[16:31]
	v_mul_f32_e64 v54, v134, v134
	v_mul_f32_e64 v55, v135, v135
	v_add_f32_e64 v52, v78, v64
	v_add_f32_e64 v53, v79, v65
	v_fma_f32 v54, v90, v90, v54
	v_fma_f32 v55, v91, v91, v55
	v_bitop3_b32 v224, v212, v190, s60 bitop3:0x36
	v_pk_add_f32 v[52:53], v[54:55], v[52:53]
	v_pk_mul_f32 v[54:55], v[136:137], v[136:137]
	v_bitop3_b32 v223, v212, v190, s59 bitop3:0x36
	v_pk_fma_f32 v[54:55], v[88:89], v[88:89], v[54:55]
	s_waitcnt lgkmcnt(0)
	v_mfma_f32_32x32x16_bf16 v[32:47], v[56:59], v[148:151], v[32:47]
	v_add_f32_e64 v52, v54, v52
	v_add_f32_e64 v53, v55, v53
	v_mul_f32_e64 v54, v138, v138
	v_mul_f32_e64 v55, v139, v139
	v_add_u32_e32 v56, v83, v227
	v_pk_fma_f32 v[54:55], v[86:87], v[86:87], v[54:55]
	v_bitop3_b32 v236, v212, v221, v190 bitop3:0xde
	v_pk_add_f32 v[64:65], v[54:55], v[52:53]
	ds_read_b128 v[52:55], v56 offset:24576
	ds_read_b128 v[56:59], v56 offset:16384
	v_mfma_f32_32x32x16_bf16 v[16:31], v[48:51], v[148:151], v[16:31]
	v_mul_f32_e64 v48, v140, v140
	v_mul_f32_e64 v49, v141, v141
	v_mul_f32_e64 v50, v142, v142
	v_mul_f32_e64 v51, v143, v143
	v_fma_f32 v48, v84, v84, v48
	v_fma_f32 v49, v85, v85, v49
	v_pk_fma_f32 v[50:51], v[80:81], v[80:81], v[50:51]
	v_pk_add_f32 v[48:49], v[48:49], v[64:65]
	v_bitop3_b32 v242, v106, v221, v190 bitop3:0xde
	v_pk_add_f32 v[48:49], v[50:51], v[48:49]
	s_waitcnt lgkmcnt(0)
	v_mfma_f32_32x32x16_bf16 v[32:47], v[56:59], v[156:159], v[32:47]
	v_mul_f32_e64 v50, v144, v144
	v_mul_f32_e64 v51, v145, v145
	v_add_u32_e32 v56, v83, v226
	v_fma_f32 v50, v76, v76, v50
	v_fma_f32 v51, v77, v77, v51
	v_pk_mul_f32 v[76:77], v[146:147], v[146:147]
	v_pk_add_f32 v[64:65], v[48:49], v[50:51]
	ds_read_b128 v[48:51], v56 offset:24576
	ds_read_b128 v[56:59], v56 offset:16384
	v_bitop3_b32 v243, v107, v221, v190 bitop3:0xde
	v_mfma_f32_32x32x16_bf16 v[16:31], v[52:55], v[156:159], v[16:31]
	v_fma_f32 v52, v60, v60, v76
	v_fma_f32 v53, v61, v61, v77
	v_mul_f32_e64 v54, v180, v180
	v_mul_f32_e64 v55, v181, v181
	v_add_f32_e64 v52, v52, v64
	v_add_f32_e64 v53, v53, v65
	v_pk_fma_f32 v[54:55], v[74:75], v[74:75], v[54:55]
	s_nop 0
	v_pk_add_f32 v[52:53], v[54:55], v[52:53]
	v_pk_mul_f32 v[54:55], v[182:183], v[182:183]
	s_waitcnt lgkmcnt(0)
	v_mfma_f32_32x32x16_bf16 v[32:47], v[56:59], v[168:171], v[32:47]
	v_fma_f32 v54, v66, v66, v54
	v_fma_f32 v55, v67, v67, v55
	v_add_u32_e32 v56, v83, v225
	v_add_f32_e64 v60, v54, v52
	v_add_f32_e64 v61, v55, v53
	v_pk_mul_f32 v[52:53], v[72:73], v[72:73]
	s_nop 0
	v_pk_fma_f32 v[62:63], v[62:63], v[62:63], v[52:53]
	ds_read_b128 v[52:55], v56 offset:24576
	ds_read_b128 v[56:59], v56 offset:16384
	v_mfma_f32_32x32x16_bf16 v[16:31], v[48:51], v[168:171], v[16:31]
	v_add_f32_e64 v48, v63, v60
	v_add_f32_e64 v49, v62, v61
	v_mul_f32_e64 v50, v184, v184
	v_mul_f32_e64 v51, v185, v185
	v_add_f32_e64 v48, v62, v48
	v_add_f32_e64 v49, v63, v49
	v_pk_fma_f32 v[50:51], v[68:69], v[68:69], v[50:51]
	v_lshlrev_b32_e32 v60, 3, v208
	v_pk_add_f32 v[48:49], v[50:51], v[48:49] op_sel:[1,0] op_sel_hi:[0,1]
	v_pk_add_f32 v[64:65], v[50:51], v[48:49]
	s_waitcnt lgkmcnt(0)
	v_mfma_f32_32x32x16_bf16 v[32:47], v[56:59], v[176:179], v[32:47]
	v_and_b32_e32 v48, 0xc0, v82
	v_add_u32_e32 v56, v83, v224
	v_and_or_b32 v61, v60, 24, v48
	v_lshlrev_b32_e32 v62, 1, v186
	ds_read_b128 v[48:51], v56 offset:24576
	ds_read_b128 v[56:59], v56 offset:16384
	v_or_b32_e32 v65, 0xa0, v212
	v_bitop3_b32 v241, v65, v221, v190 bitop3:0xde
	v_mfma_f32_32x32x16_bf16 v[16:31], v[52:55], v[176:179], v[16:31]
	v_and_b32_e32 v52, 32, v62
	v_and_b32_e32 v53, 0x100, v60
	v_or3_b32 v52, v61, v52, v53
	v_add_u32_e32 v235, s6, v52
	v_add_u32_e32 v52, 64, v189
	v_mad_i64_i32 v[52:53], s[6:7], v52, s61, v[70:71]
	v_add_u32_e32 v62, 0x60, v189
	s_waitcnt lgkmcnt(0)
	v_mfma_f32_32x32x16_bf16 v[32:47], v[56:59], v[164:167], v[32:47]
	v_lshl_add_u64 v[60:61], v[52:53], 1, s[0:1]
	v_add_u32_e32 v56, v83, v223
	ds_read_b128 v[52:55], v56 offset:24576
	ds_read_b128 v[56:59], v56 offset:16384
	v_mfma_f32_32x32x16_bf16 v[16:31], v[48:51], v[164:167], v[16:31]
	v_mad_i64_i32 v[48:49], s[6:7], v62, s61, v[70:71]
	v_lshl_add_u64 v[66:67], v[48:49], 1, s[0:1]
	global_load_dwordx4 v[48:51], v[60:61], off offset:2560
	s_nop 0
	global_load_dwordx4 v[60:63], v[60:61], off offset:2048
	s_nop 0
	global_load_dwordx4 v[98:101], v[66:67], off offset:2560
	global_load_dwordx4 v[102:105], v[66:67], off offset:2048
	v_cmp_gt_u32_e64 s[6:7], 32, v208
	s_waitcnt lgkmcnt(0)
; #define SBAR() __builtin_amdgcn_sched_barrier(0)
; #define SLOAD(k0) do { sr_.vs0 = *(const bf16x8*)(&Vh[(long)((k0) + sr) * LDK + sc]); sr_.vs1 = *(const bf16x8*)(&Vh[(long)((k0) + 32 + sr) * LDK + sc]); \
;     sr_.ks0 = *(const bf16x8*)(&Kh[(long)((k0) + sr) * LDK + sc]); sr_.ks1 = *(const bf16x8*)(&Kh[(long)((k0) + 32 + sr) * LDK + sc]); } while (0)
; #define SWRITE(so) do { *(bf16x8*)(lds + (so) + vst0) = sr_.vs0; *(bf16x8*)(lds + (so) + vst1) = sr_.vs1;          \
;     *(bf16x8*)(lds + (so) + kst0) = sr_.ks0; *(bf16x8*)(lds + (so) + kst1) = sr_.ks1; } while (0)
; #define SWAIT() asm volatile("s_waitcnt vmcnt(0)" ::: "memory")
; template <bool FIRST, bool DOEXP = true>
; __device__ __forceinline__ void partialSM(f32x16& p0, f32x16& p1, float& m_reg, f32x16& negm, float& alpha, const bool track = true) {
;     ...
;   float pmax = p0[0];
; #pragma unroll
;   for (int r = 1; r < 16; ++r) pmax = fmaxf(pmax, p0[r]);
; #pragma unroll
;   for (int r = 0; r < 16; ++r) pmax = fmaxf(pmax, p1[r]);
;   { auto rr = __builtin_amdgcn_permlane32_swap(__float_as_uint(pmax), __float_as_uint(pmax), false, false);
;     pmax = fmaxf(__uint_as_float(rr[0]), __uint_as_float(rr[1])); }
;   if (!FIRST && __builtin_expect(__all(pmax <= THRL), 1)) { alpha = 1.f; }
;   else { const float dl = FIRST ? pmax : fmaxf(pmax, 0.f); m_reg += dl; alpha = FIRST ? 1.f : __builtin_amdgcn_exp2f(-dl);
; #pragma unroll
;     for (int r = 0; r < 16; ++r) { p0[r] -= dl; p1[r] -= dl; }
; #pragma unroll
;     for (int r = 0; r < 16; ++r) negm[r] = -m_reg;
;     asm volatile("" : "+v"(negm)); }
;   if (DOEXP) {
; #pragma unroll
;     for (int r = 0; r < 16; ++r) p0[r] = __builtin_amdgcn_exp2f(p0[r]); }
; __device__ __forceinline__ void attn_item(const bf16_t* __restrict__ Qb, const bf16_t* __restrict__ Kh, const bf16_t* __restrict__ Vh, const bf16_t* __restrict__ Zb, ...
;     ...
;   { auto rr = __builtin_amdgcn_permlane32_swap(__float_as_uint(qn2), __float_as_uint(qn2), false, false); qn2 = __uint_as_float(rr[0]) + __uint_as_float(rr[1]); }
;   const bool track = !__all(__builtin_sqrtf(qn2) * kmaxg - m_reg <= 90.f);
;   SWAIT(); SWRITE(SLOT); __syncthreads();
;   for (int j = 1; j + 1 < NT; j += 2) {
;     SBAR(); SLOAD((j + 1) * KVBLK); SBAR();
	v_mfma_f32_32x32x16_bf16 v[32:47], v[56:59], v[172:175], v[32:47]
	v_or_b32_e32 v56, 32, v212
	v_or_b32_e32 v57, 64, v212
	v_or_b32_e32 v58, 0x60, v212
	v_or_b32_e32 v59, 0x80, v212
	v_bitop3_b32 v237, v56, v221, v190 bitop3:0xde
	v_bitop3_b32 v238, v57, v221, v190 bitop3:0xde
	v_bitop3_b32 v239, v58, v221, v190 bitop3:0xde
	v_mfma_f32_32x32x16_bf16 v[16:31], v[52:55], v[172:175], v[16:31]
	s_nop 3
	v_max_f32_e32 v52, v32, v33
	v_max3_f32 v52, v52, v34, v35
	v_max3_f32 v52, v52, v36, v37
	v_max3_f32 v52, v52, v38, v39
	v_max3_f32 v52, v52, v40, v41
	v_max3_f32 v52, v52, v42, v43
	v_max3_f32 v52, v52, v44, v45
	v_max3_f32 v52, v52, v46, v47
	v_max3_f32 v52, v52, v16, v17
	v_max3_f32 v52, v52, v18, v19
	v_max3_f32 v52, v52, v20, v21
	v_max3_f32 v52, v52, v22, v23
	v_max3_f32 v52, v52, v24, v25
	v_max3_f32 v52, v52, v26, v27
	v_max3_f32 v52, v52, v28, v29
	v_max3_f32 v52, v52, v30, v31
	v_mov_b32_e32 v53, v52
	s_nop 1
	v_permlane32_swap_b32_e32 v52, v53
	v_max_f32_e32 v52, v52, v53
	v_sub_f32_e32 v82, v16, v52
	v_mov_b32_e32 v16, v64
	s_nop 1
	v_permlane32_swap_b32_e32 v64, v16
	v_add_f32_e32 v16, v64, v16
	v_sub_f32_e32 v83, v17, v52
	v_mul_f32_e32 v17, 0x4f800000, v16
	v_cmp_gt_f32_e32 vcc, s65, v16
	v_sub_f32_e32 v84, v18, v52
	v_sub_f32_e32 v85, v19, v52
	v_cndmask_b32_e32 v16, v16, v17, vcc
	v_sqrt_f32_e32 v17, v16
	v_add_f32_e32 v222, 0, v52
	v_sub_f32_e32 v32, v32, v52
	v_sub_f32_e32 v33, v33, v52
	v_add_u32_e32 v18, -1, v17
	v_fma_f32 v19, -v18, v17, v16
	v_cmp_ge_f32_e64 s[0:1], 0, v19
	v_add_u32_e32 v19, 1, v17
	v_sub_f32_e32 v34, v34, v52
	v_cndmask_b32_e64 v18, v17, v18, s[0:1]
	v_fma_f32 v17, -v19, v17, v16
	v_cmp_lt_f32_e64 s[0:1], 0, v17
	v_sub_f32_e32 v35, v35, v52
	v_sub_f32_e32 v36, v36, v52
	v_cndmask_b32_e64 v17, v18, v19, s[0:1]
	v_mul_f32_e32 v18, 0x37800000, v17
	v_cndmask_b32_e32 v17, v17, v18, vcc
	v_cmp_class_f32_e32 vcc, v16, v218
	v_sub_f32_e32 v37, v37, v52
	v_sub_f32_e32 v38, v38, v52
	v_cndmask_b32_e32 v16, v17, v16, vcc
	v_fma_f32 v16, v216, v16, -v222
	v_cmp_ge_f32_e32 vcc, s66, v16
	s_cmp_lg_u64 vcc, exec
	s_cselect_b64 s[0:1], -1, 0
	s_or_b32 s8, s9, s8
	v_sub_f32_e32 v39, v39, v52
	v_sub_f32_e32 v40, v40, v52
	v_sub_f32_e32 v41, v41, v52
	v_sub_f32_e32 v42, v42, v52
	v_sub_f32_e32 v43, v43, v52
	v_sub_f32_e32 v44, v44, v52
	v_sub_f32_e32 v45, v45, v52
	v_sub_f32_e32 v46, v46, v52
	v_sub_f32_e32 v47, v47, v52
	v_xor_b32_e32 v66, 0x80000000, v222
	v_mov_b32_e32 v16, s8
	v_mov_b32_e32 v17, v1
	v_and_b32_e32 v18, 15, v186
	v_mov_b32_e32 v67, v66
	v_mov_b32_e32 v68, v66
	v_mov_b32_e32 v69, v66
	v_mov_b32_e32 v70, v66
	v_mov_b32_e32 v71, v66
	v_mov_b32_e32 v72, v66
	v_mov_b32_e32 v73, v66
	v_mov_b32_e32 v74, v66
	v_mov_b32_e32 v75, v66
	v_mov_b32_e32 v76, v66
	v_mov_b32_e32 v77, v66
	v_mov_b32_e32 v78, v66
	v_mov_b32_e32 v79, v66
	v_mov_b32_e32 v80, v66
	v_mov_b32_e32 v81, v66
	v_exp_f32_e32 v114, v32
	v_exp_f32_e32 v115, v33
	v_exp_f32_e32 v116, v34
	v_exp_f32_e32 v117, v35
	v_exp_f32_e32 v118, v36
	v_exp_f32_e32 v119, v37
	v_exp_f32_e32 v120, v38
	v_exp_f32_e32 v121, v39
	v_exp_f32_e32 v122, v40
	v_exp_f32_e32 v123, v41
	v_exp_f32_e32 v124, v42
	v_exp_f32_e32 v125, v43
	v_exp_f32_e32 v126, v44
	v_exp_f32_e32 v127, v45
	v_exp_f32_e32 v128, v46
	v_exp_f32_e32 v129, v47
	v_mad_i64_i32 v[16:17], s[8:9], v189, s51, v[16:17]
	v_lshlrev_b32_e32 v18, 4, v18
	v_mov_b32_e32 v19, v1
	v_sub_f32_e32 v97, v31, v52
	v_sub_f32_e32 v96, v30, v52
	v_sub_f32_e32 v95, v29, v52
	v_sub_f32_e32 v94, v28, v52
	v_sub_f32_e32 v93, v27, v52
	v_sub_f32_e32 v92, v26, v52
	v_sub_f32_e32 v91, v25, v52
	v_sub_f32_e32 v90, v24, v52
	v_sub_f32_e32 v89, v23, v52
	v_sub_f32_e32 v88, v22, v52
	v_sub_f32_e32 v87, v21, v52
	v_sub_f32_e32 v86, v20, v52
	s_waitcnt vmcnt(0)
	s_waitcnt vmcnt(3)
	ds_write_b128 v108, v[48:51] offset:32768
	s_waitcnt vmcnt(1)
	ds_write_b128 v109, v[98:101] offset:32768
	ds_write_b128 v112, v[60:63] offset:49152
	s_waitcnt vmcnt(0)
	ds_write_b128 v113, v[102:105] offset:49152
	v_bitop3_b32 v240, v59, v221, v190 bitop3:0xde
	v_lshl_add_u64 v[16:17], v[16:17], 0, v[18:19]
	v_mov_b64_e32 v[64:65], v[14:15]
	v_mov_b64_e32 v[48:49], v[14:15]
	v_mov_b64_e32 v[32:33], v[14:15]
	v_lshl_add_u64 v[214:215], s[20:21], 0, v[16:17]
	v_mov_b64_e32 v[62:63], v[12:13]
	v_mov_b64_e32 v[60:61], v[10:11]
	v_mov_b64_e32 v[58:59], v[8:9]
	v_mov_b64_e32 v[56:57], v[6:7]
	v_mov_b64_e32 v[54:55], v[4:5]
	v_mov_b64_e32 v[52:53], v[2:3]
	v_mov_b64_e32 v[50:51], v[0:1]
	v_mov_b64_e32 v[46:47], v[12:13]
	v_mov_b64_e32 v[44:45], v[10:11]
	v_mov_b64_e32 v[42:43], v[8:9]
	v_mov_b64_e32 v[40:41], v[6:7]
	v_mov_b64_e32 v[38:39], v[4:5]
	v_mov_b64_e32 v[36:37], v[2:3]
	v_mov_b64_e32 v[34:35], v[0:1]
	v_mov_b64_e32 v[30:31], v[12:13]
	v_mov_b64_e32 v[28:29], v[10:11]
	v_mov_b64_e32 v[26:27], v[8:9]
	v_mov_b64_e32 v[24:25], v[6:7]
	v_mov_b64_e32 v[22:23], v[4:5]
	v_mov_b64_e32 v[20:21], v[2:3]
	v_mov_b64_e32 v[18:19], v[0:1]
	v_mov_b64_e32 v[16:17], v[14:15]
	v_mov_b64_e32 v[14:15], v[12:13]
	v_mov_b64_e32 v[12:13], v[10:11]
	v_mov_b64_e32 v[10:11], v[8:9]
	v_mov_b64_e32 v[8:9], v[6:7]
	v_mov_b64_e32 v[6:7], v[4:5]
	v_mov_b64_e32 v[4:5], v[2:3]
	v_mov_b64_e32 v[2:3], v[0:1]
	v_add_co_u32_e32 v248, vcc, s67, v214
	s_nop 1
	v_addc_co_u32_e32 v249, vcc, -1, v215, vcc
	v_add_co_u32_e32 v250, vcc, s68, v214
	s_nop 1
	v_addc_co_u32_e32 v251, vcc, -1, v215, vcc
	global_load_dwordx4 v[180:183], v[248:249], off
	global_load_dwordx4 v[184:187], v[248:249], off offset:-512
	global_load_dwordx4 v[192:195], v[250:251], off
	global_load_dwordx4 v[188:191], v[250:251], off offset:-512
	v_add_u32_e32 v252, 0x10000, v228
	v_add_u32_e32 v253, 0x10000, v229
	v_add_u32_e32 v254, 0x10000, v231
	v_add_u32_e32 v255, 0x10000, v232
	s_waitcnt vmcnt(0)
; #define SBAR() __builtin_amdgcn_sched_barrier(0)
; __device__ __forceinline__ unsigned cvtpk(float lo, float hi) { unsigned r; asm volatile("v_cvt_pk_bf16_f32 %0, %1, %2" : "=v"(r) : "v"(lo), "v"(hi)); return r; }
; #define SLOAD(k0) do { sr_.vs0 = *(const bf16x8*)(&Vh[(long)((k0) + sr) * LDK + sc]); sr_.vs1 = *(const bf16x8*)(&Vh[(long)((k0) + 32 + sr) * LDK + sc]); \
;     sr_.ks0 = *(const bf16x8*)(&Kh[(long)((k0) + sr) * LDK + sc]); sr_.ks1 = *(const bf16x8*)(&Kh[(long)((k0) + 32 + sr) * LDK + sc]); } while (0)
; __device__ __forceinline__ void qkt_fin(f32x16& n0, f32x16& n1, const bf16_t* Ks, const bf16x8* qr, const f32x16& negm, int r32, int hi, ...
;   float psa = 0.f, psb = 0.f; u32x4 wa, wb, wc, wd;
;     ...
; #pragma unroll
;   for (int d0 = 0; d0 < 8; ++d0) { int cb = (d0 * 16 + hi * 8) * 2;
;     bf16x8 b0 = *reinterpret_cast<const bf16x8*>((const char*)Ks + KSWZ(r32, cb));
;     bf16x8 b1 = *reinterpret_cast<const bf16x8*>((const char*)Ks + KSWZ(32 + r32, cb));
;     SBAR(); if (d0 == 0) n0 = __builtin_amdgcn_mfma_f32_32x32x16_bf16(b0, qr[0], negm, 0, 0, 0); else n0 = __builtin_amdgcn_mfma_f32_32x32x16_bf16(b0, qr[d0], n0, 0, 0, 0);
;     SBAR(); QF_CHUNK(2 * d0); SBAR();
;     if (d0 == 0) n1 = __builtin_amdgcn_mfma_f32_32x32x16_bf16(b1, qr[0], negm, 0, 0, 0); else n1 = __builtin_amdgcn_mfma_f32_32x32x16_bf16(b1, qr[d0], n1, 0, 0, 0);
;     SBAR(); QF_CHUNK(2 * d0 + 1); SBAR();
;     if (d0 == 7) { vf8_read<0>(vf0, vbv); SBAR(); } }
;     ...
;   psb += P1[15]; wd[3] = cvtpk(P1[14], P1[15]);
;   l_reg = l_reg * alpha + (psa + psb);
;   pa0 = *reinterpret_cast<bf16x8*>(&wa); pa1 = *reinterpret_cast<bf16x8*>(&wb); pa2 = *reinterpret_cast<bf16x8*>(&wc); pa3 = *reinterpret_cast<bf16x8*>(&wd);
; }
; __device__ __forceinline__ void attn_item(const bf16_t* __restrict__ Qb, const bf16_t* __restrict__ Kh, const bf16_t* __restrict__ Vh, const bf16_t* __restrict__ Zb, ...
;     ...
;   for (int j = 1; j + 1 < NT; j += 2) {
;     SBAR(); SLOAD((j + 1) * KVBLK); SBAR();
;     qkt_fin(pB0, pB1, (const bf16_t*)(lds + s_cur + KOFF), qr, negm, r32, hi, pA0, pA1, alA, l_reg, pa0, pa1, pa2, pa3, vfa, vb0 + s_prev); SBAR();
	ds_write_b128 v252, v[180:183]
	ds_write_b128 v253, v[192:195]
	ds_write_b128 v254, v[184:187] offset:16384
	ds_write_b128 v255, v[188:191] offset:16384
	v_mbcnt_lo_u32_b32 v248, -1, 0
	v_mbcnt_hi_u32_b32 v248, -1, v248
	s_lshr_b32 s79, s33, 6
	s_lshl_b32 s100, s79, 10
	s_lshl_b32 s101, s79, 11
	s_mov_b32 s76, 0x82000
	s_mov_b32 s77, 0
	v_and_b32_e32 v249, 15, v248
	v_lshrrev_b32_e32 v250, 4, v248
	v_lshl_add_u32 v250, s79, 2, v250
	v_and_b32_e32 v251, 15, v250
	v_xor_b32_e32 v251, v249, v251
	v_sub_u32_e32 v251, v251, v249
	v_lshlrev_b32_e32 v251, 4, v251
	v_add_u32_e32 v252, 0xfffbee00, v251
	v_ashrrev_i32_e32 v253, 31, v252
	v_and_b32_e32 v254, 31, v248
	v_lshrrev_b32_e32 v254, 2, v254
	v_lshl_add_u32 v254, s79, 3, v254
	v_sub_u32_e32 v254, v254, v250
	v_add_u32_e32 v254, 0xffffffe0, v254
	v_mov_b32_e32 v255, 0x2080
	v_mul_lo_u32 v254, v254, v255
	v_lshrrev_b32_e32 v255, 5, v248
	v_lshl_add_u32 v254, v255, 6, v254
	v_and_b32_e32 v255, 3, v248
	v_lshl_add_u32 v254, v255, 4, v254
	v_lshlrev_b32_e32 v255, 4, v249
	v_sub_u32_e32 v254, v254, v255
	s_waitcnt lgkmcnt(0)
	v_lshl_add_u64 v[180:181], v[214:215], 0, v[252:253]
	v_ashrrev_i32_e32 v255, 31, v254
	v_add_co_u32_e32 v182, vcc, 0x41000, v180
	s_nop 1
	v_addc_co_u32_e32 v183, vcc, 0, v181, vcc
	v_lshl_add_u64 v[214:215], v[214:215], 0, v[254:255]
	s_mov_b32 s96, 0x8000
	s_mov_b32 s8, 0
	s_cmp_ge_u32 s33, 0x100
	s_cbranch_scc1 .Lh2_pro
	s_barrier
.LBB0_453:
	s_add_i32 s97, s96, 0xffff8000
	s_xor_b32 s98, s96, 0x10000
	s_add_i32 s99, s96, 0x8000
	s_and_b32 s99, s99, 0x18000
	v_add_u32_e32 v196, s96, v236
	ds_read_b128 v[98:101], v196 offset:16384
	ds_read_b128 v[196:199], v196 offset:24576
	v_add_u32_e32 v252, s96, v237
	ds_read_b128 v[248:251], v252 offset:16384
	ds_read_b128 v[252:255], v252 offset:24576
	v_add_u32_e32 v0, s97, v235
	s_waitcnt lgkmcnt(3)
	v_mfma_f32_32x32x16_bf16 v[132:147], v[98:101], v[152:155], v[66:81]
	v_exp_f32_e32 v82, v82
	s_waitcnt lgkmcnt(2)
	v_mfma_f32_32x32x16_bf16 v[98:113], v[196:199], v[152:155], v[66:81]
	v_exp_f32_e32 v83, v83
	v_cvt_pk_bf16_f32 v196, v114, v115
	v_add_u32_e32 v206, s96, v238
	ds_read_b128 v[202:205], v206 offset:16384
	ds_read_b128 v[206:209], v206 offset:24576
	s_waitcnt lgkmcnt(3)
	v_mfma_f32_32x32x16_bf16 v[132:147], v[248:251], v[160:163], v[132:147]
	v_exp_f32_e32 v84, v84
	s_waitcnt lgkmcnt(2)
	v_mfma_f32_32x32x16_bf16 v[98:113], v[252:255], v[160:163], v[98:113]
	v_exp_f32_e32 v85, v85
	v_pk_add_f32 v[184:185], v[114:115], v[116:117]
	v_cvt_pk_bf16_f32 v197, v116, v117
	v_cvt_pk_bf16_f32 v200, v82, v83
	v_add_u32_e32 v252, s96, v239
	ds_read_b128 v[248:251], v252 offset:16384
	ds_read_b128 v[252:255], v252 offset:24576
	s_waitcnt lgkmcnt(3)
	v_mfma_f32_32x32x16_bf16 v[132:147], v[202:205], v[148:151], v[132:147]
	v_exp_f32_e32 v86, v86
	v_pk_add_f32 v[186:187], v[82:83], v[84:85]
	s_waitcnt lgkmcnt(2)
	v_mfma_f32_32x32x16_bf16 v[98:113], v[206:209], v[148:151], v[98:113]
	v_exp_f32_e32 v87, v87
	v_pk_add_f32 v[184:185], v[184:185], v[118:119]
	v_cvt_pk_bf16_f32 v198, v118, v119
	v_cvt_pk_bf16_f32 v201, v84, v85
	v_add_u32_e32 v208, s96, v240
	ds_read_b128 v[204:207], v208 offset:16384
	ds_read_b128 v[208:211], v208 offset:24576
	s_waitcnt lgkmcnt(3)
	v_mfma_f32_32x32x16_bf16 v[132:147], v[248:251], v[156:159], v[132:147]
	v_exp_f32_e32 v88, v88
	v_pk_add_f32 v[186:187], v[186:187], v[86:87]
	s_waitcnt lgkmcnt(2)
	v_mfma_f32_32x32x16_bf16 v[98:113], v[252:255], v[156:159], v[98:113]
	v_exp_f32_e32 v89, v89
	v_pk_add_f32 v[184:185], v[184:185], v[120:121]
	v_cvt_pk_bf16_f32 v199, v120, v121
	v_cvt_pk_bf16_f32 v202, v86, v87
	v_add_u32_e32 v252, s96, v241
	ds_read_b128 v[248:251], v252 offset:16384
	ds_read_b128 v[252:255], v252 offset:24576
	s_waitcnt lgkmcnt(3)
	v_mfma_f32_32x32x16_bf16 v[132:147], v[204:207], v[168:171], v[132:147]
	v_exp_f32_e32 v90, v90
	v_pk_add_f32 v[186:187], v[186:187], v[88:89]
	s_waitcnt lgkmcnt(2)
	v_mfma_f32_32x32x16_bf16 v[98:113], v[208:211], v[168:171], v[98:113]
	v_exp_f32_e32 v91, v91
	v_pk_add_f32 v[184:185], v[184:185], v[122:123]
	v_cvt_pk_bf16_f32 v204, v122, v123
	v_cvt_pk_bf16_f32 v203, v88, v89
	v_add_u32_e32 v118, s96, v242
	ds_read_b128 v[114:117], v118 offset:16384
	ds_read_b128 v[118:121], v118 offset:24576
	s_waitcnt lgkmcnt(3)
	v_mfma_f32_32x32x16_bf16 v[132:147], v[248:251], v[176:179], v[132:147]
	v_exp_f32_e32 v92, v92
	v_pk_add_f32 v[186:187], v[186:187], v[90:91]
	s_waitcnt lgkmcnt(2)
	v_mfma_f32_32x32x16_bf16 v[98:113], v[252:255], v[176:179], v[98:113]
	v_exp_f32_e32 v93, v93
	v_pk_add_f32 v[184:185], v[184:185], v[124:125]
	v_cvt_pk_bf16_f32 v205, v124, v125
	v_cvt_pk_bf16_f32 v208, v90, v91
	v_add_u32_e32 v252, s96, v243
	ds_read_b128 v[248:251], v252 offset:16384
	ds_read_b128 v[252:255], v252 offset:24576
	s_waitcnt lgkmcnt(3)
	v_mfma_f32_32x32x16_bf16 v[132:147], v[114:117], v[164:167], v[132:147]
	v_exp_f32_e32 v94, v94
	v_pk_add_f32 v[186:187], v[186:187], v[92:93]
	s_waitcnt lgkmcnt(2)
	v_mfma_f32_32x32x16_bf16 v[98:113], v[118:121], v[164:167], v[98:113]
	v_exp_f32_e32 v95, v95
	v_pk_add_f32 v[184:185], v[184:185], v[126:127]
	v_cvt_pk_bf16_f32 v206, v126, v127
	v_cvt_pk_bf16_f32 v209, v92, v93
	s_waitcnt lgkmcnt(1)
	v_mfma_f32_32x32x16_bf16 v[132:147], v[248:251], v[172:175], v[132:147]
	v_exp_f32_e32 v96, v96
	v_pk_add_f32 v[186:187], v[186:187], v[94:95]
	s_waitcnt lgkmcnt(0)
	v_mfma_f32_32x32x16_bf16 v[98:113], v[252:255], v[172:175], v[98:113]
	v_exp_f32_e32 v97, v97
	v_pk_add_f32 v[184:185], v[184:185], v[128:129]
	v_add_f32_e32 v245, v184, v185
	v_add_f32_e32 v246, v186, v187
	v_add_f32_e32 v246, v246, v96
	v_cvt_pk_bf16_f32 v207, v128, v129
	v_cvt_pk_bf16_f32 v210, v94, v95
	v_mov_b32_e32 v131, v97
	v_cvt_pk_bf16_f32 v211, v96, v97
	ds_read_b64_tr_b16 v[94:95], v0 offset:0
	ds_read_b64_tr_b16 v[96:97], v0 offset:2048
	ds_read_b64_tr_b16 v[90:91], v0 offset:4096
	ds_read_b64_tr_b16 v[92:93], v0 offset:6144
	ds_read_b64_tr_b16 v[86:87], v0 offset:8192
	ds_read_b64_tr_b16 v[88:89], v0 offset:10240
	ds_read_b64_tr_b16 v[82:83], v0 offset:12288
	ds_read_b64_tr_b16 v[84:85], v0 offset:14336
	v_cndmask_b32_e64 v114, 0, 1, s[0:1]
	v_cmp_ne_u32_e64 s[8:9], 1, v114
	s_andn2_b64 vcc, exec, s[0:1]
	s_cbranch_vccnz .LBB0_456
; template <bool FIRST, bool DOEXP = true>
; __device__ __forceinline__ void partialSM(f32x16& p0, f32x16& p1, float& m_reg, f32x16& negm, float& alpha, const bool track = true) {
;   if (!FIRST && !track) { alpha = 1.f;
;     if (DOEXP) {
; #pragma unroll
;       for (int r = 0; r < 16; ++r) p0[r] = __builtin_amdgcn_exp2f(p0[r]); }
;     return; }
;   float pmax = p0[0];
; #pragma unroll
;   for (int r = 1; r < 16; ++r) pmax = fmaxf(pmax, p0[r]);
; #pragma unroll
;   for (int r = 0; r < 16; ++r) pmax = fmaxf(pmax, p1[r]);
;   { auto rr = __builtin_amdgcn_permlane32_swap(__float_as_uint(pmax), __float_as_uint(pmax), false, false);
;     pmax = fmaxf(__uint_as_float(rr[0]), __uint_as_float(rr[1])); }
;   if (!FIRST && __builtin_expect(__all(pmax <= THRL), 1)) { alpha = 1.f; }
;   else { const float dl = FIRST ? pmax : fmaxf(pmax, 0.f); m_reg += dl; alpha = FIRST ? 1.f : __builtin_amdgcn_exp2f(-dl);
; #pragma unroll
;     for (int r = 0; r < 16; ++r) { p0[r] -= dl; p1[r] -= dl; }
; #pragma unroll
;     for (int r = 0; r < 16; ++r) negm[r] = -m_reg;
;     asm volatile("" : "+v"(negm)); }
	v_max_f32_e32 v114, v132, v133
	v_max3_f32 v114, v114, v134, v135
	v_max3_f32 v114, v114, v136, v137
	v_max3_f32 v114, v114, v138, v139
	v_max3_f32 v114, v114, v140, v141
	v_max3_f32 v114, v114, v142, v143
	v_max3_f32 v114, v114, v144, v145
	v_max3_f32 v114, v114, v146, v147
	v_max3_f32 v114, v114, v98, v99
	v_max3_f32 v114, v114, v100, v101
	v_max3_f32 v114, v114, v102, v103
	v_max3_f32 v114, v114, v104, v105
	v_max3_f32 v114, v114, v106, v107
	v_max3_f32 v114, v114, v108, v109
	v_max3_f32 v114, v114, v110, v111
	v_max3_f32 v114, v114, v112, v113
	v_mov_b32_e32 v115, v114
	s_nop 1
	v_permlane32_swap_b32_e32 v114, v115
	v_max_f32_e32 v114, v114, v115
	v_cmp_ge_f32_e32 vcc, s69, v114
	s_cmp_eq_u64 vcc, exec
	v_mov_b32_e32 v130, 1.0
	s_cbranch_scc1 .LBB0_457
	v_max_f32_e32 v66, v114, v114
	v_max_f32_e32 v66, 0, v66
	v_exp_f32_e64 v130, -v66
	v_add_f32_e32 v222, v222, v66
	v_sub_f32_e32 v147, v147, v66
	v_sub_f32_e32 v146, v146, v66
	v_sub_f32_e32 v145, v145, v66
	v_sub_f32_e32 v144, v144, v66
	v_sub_f32_e32 v143, v143, v66
	v_sub_f32_e32 v142, v142, v66
	v_sub_f32_e32 v141, v141, v66
	v_sub_f32_e32 v140, v140, v66
	v_sub_f32_e32 v139, v139, v66
	v_sub_f32_e32 v138, v138, v66
	v_sub_f32_e32 v137, v137, v66
	v_sub_f32_e32 v136, v136, v66
	v_sub_f32_e32 v135, v135, v66
	v_sub_f32_e32 v134, v134, v66
	v_sub_f32_e32 v133, v133, v66
	v_sub_f32_e32 v132, v132, v66
	v_sub_f32_e32 v113, v113, v66
	v_sub_f32_e32 v112, v112, v66
	v_sub_f32_e32 v111, v111, v66
	v_sub_f32_e32 v110, v110, v66
	v_sub_f32_e32 v109, v109, v66
	v_sub_f32_e32 v108, v108, v66
	v_sub_f32_e32 v107, v107, v66
	v_sub_f32_e32 v106, v106, v66
	v_sub_f32_e32 v105, v105, v66
	v_sub_f32_e32 v104, v104, v66
	v_sub_f32_e32 v103, v103, v66
	v_sub_f32_e32 v102, v102, v66
	v_sub_f32_e32 v101, v101, v66
	v_sub_f32_e32 v100, v100, v66
	v_sub_f32_e32 v99, v99, v66
	v_sub_f32_e32 v98, v98, v66
	v_xor_b32_e32 v66, 0x80000000, v222
	v_mov_b32_e32 v67, v66
	v_mov_b32_e32 v68, v66
	v_mov_b32_e32 v69, v66
	v_mov_b32_e32 v70, v66
	v_mov_b32_e32 v71, v66
	v_mov_b32_e32 v72, v66
	v_mov_b32_e32 v73, v66
	v_mov_b32_e32 v74, v66
	v_mov_b32_e32 v75, v66
	v_mov_b32_e32 v76, v66
	v_mov_b32_e32 v77, v66
	v_mov_b32_e32 v78, v66
	v_mov_b32_e32 v79, v66
	v_mov_b32_e32 v80, v66
	v_mov_b32_e32 v81, v66
	s_branch .LBB0_457

; #define SBAR() __builtin_amdgcn_sched_barrier(0)
; template <bool FIRST, bool DOEXP = true>
; __device__ __forceinline__ void partialSM(f32x16& p0, f32x16& p1, float& m_reg, f32x16& negm, float& alpha, const bool track = true) {
;   if (!FIRST && !track) { alpha = 1.f;
;     if (DOEXP) {
; #pragma unroll
;       for (int r = 0; r < 16; ++r) p0[r] = __builtin_amdgcn_exp2f(p0[r]); }
;     return; }
;   float pmax = p0[0];
; #pragma unroll
;   for (int r = 1; r < 16; ++r) pmax = fmaxf(pmax, p0[r]);
; #pragma unroll
;   for (int r = 0; r < 16; ++r) pmax = fmaxf(pmax, p1[r]);
;   { auto rr = __builtin_amdgcn_permlane32_swap(__float_as_uint(pmax), __float_as_uint(pmax), false, false);
;     pmax = fmaxf(__uint_as_float(rr[0]), __uint_as_float(rr[1])); }
;   if (!FIRST && __builtin_expect(__all(pmax <= THRL), 1)) { alpha = 1.f; }
;   else { const float dl = FIRST ? pmax : fmaxf(pmax, 0.f); m_reg += dl; alpha = FIRST ? 1.f : __builtin_amdgcn_exp2f(-dl);
; #pragma unroll
;     for (int r = 0; r < 16; ++r) { p0[r] -= dl; p1[r] -= dl; }
; #pragma unroll
;     for (int r = 0; r < 16; ++r) negm[r] = -m_reg;
;     asm volatile("" : "+v"(negm)); }
; __device__ __forceinline__ void qkt_fin(f32x16& n0, f32x16& n1, const bf16_t* Ks, const bf16x8* qr, const f32x16& negm, int r32, int hi, ...
;   float psa = 0.f, psb = 0.f; u32x4 wa, wb, wc, wd;
;     ...
; #pragma unroll
;   for (int d0 = 0; d0 < 8; ++d0) { int cb = (d0 * 16 + hi * 8) * 2;
;     bf16x8 b0 = *reinterpret_cast<const bf16x8*>((const char*)Ks + KSWZ(r32, cb));
;     bf16x8 b1 = *reinterpret_cast<const bf16x8*>((const char*)Ks + KSWZ(32 + r32, cb));
;     SBAR(); if (d0 == 0) n0 = __builtin_amdgcn_mfma_f32_32x32x16_bf16(b0, qr[0], negm, 0, 0, 0); else n0 = __builtin_amdgcn_mfma_f32_32x32x16_bf16(b0, qr[d0], n0, 0, 0, 0);
;     SBAR(); QF_CHUNK(2 * d0); SBAR();
;     if (d0 == 0) n1 = __builtin_amdgcn_mfma_f32_32x32x16_bf16(b1, qr[0], negm, 0, 0, 0); else n1 = __builtin_amdgcn_mfma_f32_32x32x16_bf16(b1, qr[d0], n1, 0, 0, 0);
;     SBAR(); QF_CHUNK(2 * d0 + 1); SBAR();
;     if (d0 == 7) { vf8_read<0>(vf0, vbv); SBAR(); } }
;     ...
;   psb += P1[15]; wd[3] = cvtpk(P1[14], P1[15]);
;   l_reg = l_reg * alpha + (psa + psb);
;   pa0 = *reinterpret_cast<bf16x8*>(&wa); pa1 = *reinterpret_cast<bf16x8*>(&wb); pa2 = *reinterpret_cast<bf16x8*>(&wc); pa3 = *reinterpret_cast<bf16x8*>(&wd);
; }
.LBB0_461:
	s_waitcnt lgkmcnt(0)
	v_add_u32_e32 v208, s99, v236
	ds_read_b128 v[204:207], v208 offset:16384
	ds_read_b128 v[208:211], v208 offset:24576
	v_add_u32_e32 v252, s99, v237
	ds_read_b128 v[248:251], v252 offset:16384
	ds_read_b128 v[252:255], v252 offset:24576
	v_add_u32_e32 v203, s96, v235
	s_waitcnt lgkmcnt(3)
	v_mfma_f32_32x32x16_bf16 v[114:129], v[204:207], v[152:155], v[66:81]
	v_exp_f32_e32 v98, v98
	s_waitcnt lgkmcnt(2)
	v_mfma_f32_32x32x16_bf16 v[82:97], v[208:211], v[152:155], v[66:81]
	v_exp_f32_e32 v99, v99
	v_cvt_pk_bf16_f32 v132, v132, v133
	v_add_u32_e32 v208, s99, v238
	ds_read_b128 v[204:207], v208 offset:16384
	ds_read_b128 v[208:211], v208 offset:24576
	s_waitcnt lgkmcnt(3)
	v_mfma_f32_32x32x16_bf16 v[114:129], v[248:251], v[160:163], v[114:129]
	v_exp_f32_e32 v100, v100
	s_waitcnt lgkmcnt(2)
	v_mfma_f32_32x32x16_bf16 v[82:97], v[252:255], v[160:163], v[82:97]
	v_exp_f32_e32 v101, v101
	v_pk_add_f32 v[184:185], v[132:133], v[134:135]
	v_cvt_pk_bf16_f32 v133, v134, v135
	v_cvt_pk_bf16_f32 v196, v98, v99
	v_add_u32_e32 v252, s99, v239
	ds_read_b128 v[248:251], v252 offset:16384
	ds_read_b128 v[252:255], v252 offset:24576
	s_waitcnt lgkmcnt(3)
	v_mfma_f32_32x32x16_bf16 v[114:129], v[204:207], v[148:151], v[114:129]
	v_exp_f32_e32 v102, v102
	v_pk_add_f32 v[186:187], v[98:99], v[100:101]
	s_waitcnt lgkmcnt(2)
	v_mfma_f32_32x32x16_bf16 v[82:97], v[208:211], v[148:151], v[82:97]
	v_exp_f32_e32 v103, v103
	v_pk_add_f32 v[184:185], v[184:185], v[136:137]
	v_cvt_pk_bf16_f32 v134, v136, v137
	v_cvt_pk_bf16_f32 v197, v100, v101
	v_add_u32_e32 v208, s99, v240
	ds_read_b128 v[204:207], v208 offset:16384
	ds_read_b128 v[208:211], v208 offset:24576
	s_waitcnt lgkmcnt(3)
	v_mfma_f32_32x32x16_bf16 v[114:129], v[248:251], v[156:159], v[114:129]
	v_exp_f32_e32 v104, v104
	v_pk_add_f32 v[186:187], v[186:187], v[102:103]
	s_waitcnt lgkmcnt(2)
	v_mfma_f32_32x32x16_bf16 v[82:97], v[252:255], v[156:159], v[82:97]
	v_exp_f32_e32 v105, v105
	v_pk_add_f32 v[184:185], v[184:185], v[138:139]
	v_cvt_pk_bf16_f32 v135, v138, v139
	v_cvt_pk_bf16_f32 v198, v102, v103
	v_add_u32_e32 v252, s99, v241
	ds_read_b128 v[248:251], v252 offset:16384
	ds_read_b128 v[252:255], v252 offset:24576
	s_waitcnt lgkmcnt(3)
	v_mfma_f32_32x32x16_bf16 v[114:129], v[204:207], v[168:171], v[114:129]
	v_exp_f32_e32 v106, v106
	v_pk_add_f32 v[186:187], v[186:187], v[104:105]
	s_waitcnt lgkmcnt(2)
	v_mfma_f32_32x32x16_bf16 v[82:97], v[208:211], v[168:171], v[82:97]
	v_exp_f32_e32 v107, v107
	v_pk_add_f32 v[184:185], v[184:185], v[140:141]
	v_cvt_pk_bf16_f32 v136, v140, v141
	v_cvt_pk_bf16_f32 v199, v104, v105
	v_add_u32_e32 v208, s99, v242
	ds_read_b128 v[204:207], v208 offset:16384
	ds_read_b128 v[208:211], v208 offset:24576
	s_waitcnt lgkmcnt(3)
	v_mfma_f32_32x32x16_bf16 v[114:129], v[248:251], v[176:179], v[114:129]
	v_exp_f32_e32 v108, v108
	v_pk_add_f32 v[186:187], v[186:187], v[106:107]
	s_waitcnt lgkmcnt(2)
	v_mfma_f32_32x32x16_bf16 v[82:97], v[252:255], v[176:179], v[82:97]
	v_exp_f32_e32 v109, v109
	v_pk_add_f32 v[184:185], v[184:185], v[142:143]
	v_cvt_pk_bf16_f32 v137, v142, v143
	v_cvt_pk_bf16_f32 v140, v106, v107
	v_add_u32_e32 v252, s99, v243
	ds_read_b128 v[248:251], v252 offset:16384
	ds_read_b128 v[252:255], v252 offset:24576
	s_waitcnt lgkmcnt(3)
	v_mfma_f32_32x32x16_bf16 v[114:129], v[204:207], v[164:167], v[114:129]
	v_exp_f32_e32 v110, v110
	v_pk_add_f32 v[186:187], v[186:187], v[108:109]
	s_waitcnt lgkmcnt(2)
	v_mfma_f32_32x32x16_bf16 v[82:97], v[208:211], v[164:167], v[82:97]
	v_exp_f32_e32 v111, v111
	v_pk_add_f32 v[184:185], v[184:185], v[144:145]
	v_cvt_pk_bf16_f32 v138, v144, v145
	v_cvt_pk_bf16_f32 v141, v108, v109
	s_waitcnt lgkmcnt(1)
	v_mfma_f32_32x32x16_bf16 v[114:129], v[248:251], v[172:175], v[114:129]
	v_exp_f32_e32 v112, v112
	v_pk_add_f32 v[186:187], v[186:187], v[110:111]
	s_waitcnt lgkmcnt(0)
	v_mfma_f32_32x32x16_bf16 v[82:97], v[252:255], v[172:175], v[82:97]
	v_exp_f32_e32 v113, v113
	v_pk_add_f32 v[184:185], v[184:185], v[146:147]
	v_add_f32_e32 v201, v184, v185
	v_add_f32_e32 v202, v186, v187
	v_add_f32_e32 v202, v202, v112
	v_cvt_pk_bf16_f32 v139, v146, v147
	v_cvt_pk_bf16_f32 v142, v110, v111
	ds_read_b64_tr_b16 v[144:145], v203 offset:0
	ds_read_b64_tr_b16 v[146:147], v203 offset:2048
	s_nop 0
	ds_read_b64_tr_b16 v[106:107], v203 offset:4096
	ds_read_b64_tr_b16 v[108:109], v203 offset:6144
	ds_read_b64_tr_b16 v[102:103], v203 offset:8192
	ds_read_b64_tr_b16 v[104:105], v203 offset:10240
	ds_read_b64_tr_b16 v[98:99], v203 offset:12288
	ds_read_b64_tr_b16 v[100:101], v203 offset:14336
	v_cvt_pk_bf16_f32 v143, v112, v113
	s_and_b64 vcc, exec, s[8:9]
	v_mov_b32_e32 v200, 1.0
	s_cbranch_vccnz .LBB0_463
	v_max_f32_e32 v110, v114, v115
	v_max3_f32 v110, v110, v116, v117
	v_max3_f32 v110, v110, v118, v119
	v_max3_f32 v110, v110, v120, v121
	v_max3_f32 v110, v110, v122, v123
	v_max3_f32 v110, v110, v124, v125
	v_max3_f32 v110, v110, v126, v127
	v_max3_f32 v110, v110, v128, v129
	v_max3_f32 v110, v110, v82, v83
	v_max3_f32 v110, v110, v84, v85
	v_max3_f32 v110, v110, v86, v87
	v_max3_f32 v110, v110, v88, v89
	v_max3_f32 v110, v110, v90, v91
	v_max3_f32 v110, v110, v92, v93
	v_max3_f32 v110, v110, v94, v95
	v_max3_f32 v110, v110, v96, v97
	v_mov_b32_e32 v111, v110
	s_nop 1
	v_permlane32_swap_b32_e32 v110, v111
	v_max_f32_e32 v110, v110, v111
	v_cmp_ge_f32_e32 vcc, s69, v110
	s_cmp_eq_u64 vcc, exec
	v_mov_b32_e32 v200, 1.0
	s_cbranch_scc0 .LBB0_469

; #define SBAR() __builtin_amdgcn_sched_barrier(0)
; __device__ __forceinline__ unsigned cvtpk(float lo, float hi) { unsigned r; asm volatile("v_cvt_pk_bf16_f32 %0, %1, %2" : "=v"(r) : "v"(lo), "v"(hi)); return r; }
; __device__ __forceinline__ void qkt_fin(f32x16& n0, f32x16& n1, const bf16_t* Ks, const bf16x8* qr, const f32x16& negm, int r32, int hi, ...
;   float psa = 0.f, psb = 0.f; u32x4 wa, wb, wc, wd;
;     ...
; #pragma unroll
;   for (int d0 = 0; d0 < 8; ++d0) { int cb = (d0 * 16 + hi * 8) * 2;
;     bf16x8 b0 = *reinterpret_cast<const bf16x8*>((const char*)Ks + KSWZ(r32, cb));
;     bf16x8 b1 = *reinterpret_cast<const bf16x8*>((const char*)Ks + KSWZ(32 + r32, cb));
;     SBAR(); if (d0 == 0) n0 = __builtin_amdgcn_mfma_f32_32x32x16_bf16(b0, qr[0], negm, 0, 0, 0); else n0 = __builtin_amdgcn_mfma_f32_32x32x16_bf16(b0, qr[d0], n0, 0, 0, 0);
;     SBAR(); QF_CHUNK(2 * d0); SBAR();
;     if (d0 == 0) n1 = __builtin_amdgcn_mfma_f32_32x32x16_bf16(b1, qr[0], negm, 0, 0, 0); else n1 = __builtin_amdgcn_mfma_f32_32x32x16_bf16(b1, qr[d0], n1, 0, 0, 0);
;     SBAR(); QF_CHUNK(2 * d0 + 1); SBAR();
;     if (d0 == 7) { vf8_read<0>(vf0, vbv); SBAR(); } }
;     ...
;   psb += P1[15]; wd[3] = cvtpk(P1[14], P1[15]);
;   l_reg = l_reg * alpha + (psa + psb);
;   pa0 = *reinterpret_cast<bf16x8*>(&wa); pa1 = *reinterpret_cast<bf16x8*>(&wb); pa2 = *reinterpret_cast<bf16x8*>(&wc); pa3 = *reinterpret_cast<bf16x8*>(&wd);
; }
.Lh2_453:
	s_setprio 1
	s_add_i32 s97, s96, 0xffff8000
	s_xor_b32 s98, s96, 0x10000
	s_add_i32 s99, s96, 0x8000
	s_and_b32 s99, s99, 0x18000
	v_add_u32_e32 v196, s96, v236
	ds_read_b128 v[98:101], v196 offset:16384
	ds_read_b128 v[196:199], v196 offset:24576
	v_add_u32_e32 v252, s96, v237
	ds_read_b128 v[248:251], v252 offset:16384
	ds_read_b128 v[252:255], v252 offset:24576
	v_add_u32_e32 v0, s97, v235
	s_waitcnt lgkmcnt(3)
	v_mfma_f32_32x32x16_bf16 v[132:147], v[98:101], v[152:155], v[66:81]
	v_exp_f32_e32 v82, v82
	s_waitcnt lgkmcnt(2)
	v_mfma_f32_32x32x16_bf16 v[98:113], v[196:199], v[152:155], v[66:81]
	v_exp_f32_e32 v83, v83
	v_cvt_pk_bf16_f32 v196, v114, v115
	v_add_u32_e32 v206, s96, v238
	ds_read_b128 v[202:205], v206 offset:16384
	ds_read_b128 v[206:209], v206 offset:24576
	s_waitcnt lgkmcnt(3)
	v_mfma_f32_32x32x16_bf16 v[132:147], v[248:251], v[160:163], v[132:147]
	v_exp_f32_e32 v84, v84
	s_waitcnt lgkmcnt(2)
	v_mfma_f32_32x32x16_bf16 v[98:113], v[252:255], v[160:163], v[98:113]
	v_exp_f32_e32 v85, v85
	v_pk_add_f32 v[184:185], v[114:115], v[116:117]
	v_cvt_pk_bf16_f32 v197, v116, v117
	v_cvt_pk_bf16_f32 v200, v82, v83
	v_add_u32_e32 v252, s96, v239
	ds_read_b128 v[248:251], v252 offset:16384
	ds_read_b128 v[252:255], v252 offset:24576
	s_add_i32 s79, s99, s100
	s_add_i32 m0, s79, 0x4000
	s_add_i32 s79, s79, 0x6000
	global_load_lds_dwordx4 v[180:181], off
	s_waitcnt lgkmcnt(3)
	v_mfma_f32_32x32x16_bf16 v[132:147], v[202:205], v[148:151], v[132:147]
	v_exp_f32_e32 v86, v86
	v_pk_add_f32 v[186:187], v[82:83], v[84:85]
	s_waitcnt lgkmcnt(2)
	v_mfma_f32_32x32x16_bf16 v[98:113], v[206:209], v[148:151], v[98:113]
	v_exp_f32_e32 v87, v87
	v_pk_add_f32 v[184:185], v[184:185], v[118:119]
	v_cvt_pk_bf16_f32 v198, v118, v119
	v_cvt_pk_bf16_f32 v201, v84, v85
	v_add_u32_e32 v208, s96, v240
	ds_read_b128 v[204:207], v208 offset:16384
	ds_read_b128 v[208:211], v208 offset:24576
	s_mov_b32 m0, s79
	s_add_i32 s79, s99, s101
	global_load_lds_dwordx4 v[182:183], off
	s_waitcnt lgkmcnt(3)
	v_mfma_f32_32x32x16_bf16 v[132:147], v[248:251], v[156:159], v[132:147]
	v_exp_f32_e32 v88, v88
	v_pk_add_f32 v[186:187], v[186:187], v[86:87]
	s_waitcnt lgkmcnt(2)
	v_mfma_f32_32x32x16_bf16 v[98:113], v[252:255], v[156:159], v[98:113]
	v_exp_f32_e32 v89, v89
	v_pk_add_f32 v[184:185], v[184:185], v[120:121]
	v_cvt_pk_bf16_f32 v199, v120, v121
	v_cvt_pk_bf16_f32 v202, v86, v87
	v_add_u32_e32 v252, s96, v241
	ds_read_b128 v[248:251], v252 offset:16384
	ds_read_b128 v[252:255], v252 offset:24576
	s_mov_b32 m0, s79
	s_add_i32 s79, s79, 0x380
	global_load_lds_dwordx4 v[214:215], off
	s_waitcnt lgkmcnt(3)
	v_mfma_f32_32x32x16_bf16 v[132:147], v[204:207], v[168:171], v[132:147]
	v_exp_f32_e32 v90, v90
	v_pk_add_f32 v[186:187], v[186:187], v[88:89]
	s_waitcnt lgkmcnt(2)
	v_mfma_f32_32x32x16_bf16 v[98:113], v[208:211], v[168:171], v[98:113]
	v_exp_f32_e32 v91, v91
	v_pk_add_f32 v[184:185], v[184:185], v[122:123]
	v_cvt_pk_bf16_f32 v204, v122, v123
	v_cvt_pk_bf16_f32 v203, v88, v89
	v_add_u32_e32 v118, s96, v242
	ds_read_b128 v[114:117], v118 offset:16384
	ds_read_b128 v[118:121], v118 offset:24576
	s_mov_b32 m0, s79
	s_nop 0
	global_load_lds_dwordx4 v[214:215], off offset:128
	v_lshl_add_u64 v[180:181], v[180:181], 0, s[76:77]
	v_lshl_add_u64 v[182:183], v[182:183], 0, s[76:77]
	v_lshl_add_u64 v[214:215], v[214:215], 0, s[76:77]
	s_waitcnt lgkmcnt(3)
	v_mfma_f32_32x32x16_bf16 v[132:147], v[248:251], v[176:179], v[132:147]
	v_exp_f32_e32 v92, v92
	v_pk_add_f32 v[186:187], v[186:187], v[90:91]
	s_waitcnt lgkmcnt(2)
	v_mfma_f32_32x32x16_bf16 v[98:113], v[252:255], v[176:179], v[98:113]
	v_exp_f32_e32 v93, v93
	v_pk_add_f32 v[184:185], v[184:185], v[124:125]
	v_cvt_pk_bf16_f32 v205, v124, v125
	v_cvt_pk_bf16_f32 v208, v90, v91
	v_add_u32_e32 v252, s96, v243
	ds_read_b128 v[248:251], v252 offset:16384
	ds_read_b128 v[252:255], v252 offset:24576
	s_waitcnt lgkmcnt(3)
	v_mfma_f32_32x32x16_bf16 v[132:147], v[114:117], v[164:167], v[132:147]
	v_exp_f32_e32 v94, v94
	v_pk_add_f32 v[186:187], v[186:187], v[92:93]
	s_waitcnt lgkmcnt(2)
	v_mfma_f32_32x32x16_bf16 v[98:113], v[118:121], v[164:167], v[98:113]
	v_exp_f32_e32 v95, v95
	v_pk_add_f32 v[184:185], v[184:185], v[126:127]
	v_cvt_pk_bf16_f32 v206, v126, v127
	v_cvt_pk_bf16_f32 v209, v92, v93
	s_waitcnt lgkmcnt(1)
	v_mfma_f32_32x32x16_bf16 v[132:147], v[248:251], v[172:175], v[132:147]
	v_exp_f32_e32 v96, v96
	v_pk_add_f32 v[186:187], v[186:187], v[94:95]
	s_waitcnt lgkmcnt(0)
	v_mfma_f32_32x32x16_bf16 v[98:113], v[252:255], v[172:175], v[98:113]
	v_exp_f32_e32 v97, v97
	v_pk_add_f32 v[184:185], v[184:185], v[128:129]
	v_add_f32_e32 v245, v184, v185
	v_add_f32_e32 v246, v186, v187
	v_add_f32_e32 v246, v246, v96
	v_cvt_pk_bf16_f32 v207, v128, v129
	v_cvt_pk_bf16_f32 v210, v94, v95
	v_mov_b32_e32 v131, v97
	v_cvt_pk_bf16_f32 v211, v96, v97
	ds_read_b64_tr_b16 v[94:95], v0 offset:0
	ds_read_b64_tr_b16 v[96:97], v0 offset:2048
	ds_read_b64_tr_b16 v[90:91], v0 offset:4096
	ds_read_b64_tr_b16 v[92:93], v0 offset:6144
	ds_read_b64_tr_b16 v[86:87], v0 offset:8192
	ds_read_b64_tr_b16 v[88:89], v0 offset:10240
	ds_read_b64_tr_b16 v[82:83], v0 offset:12288
	ds_read_b64_tr_b16 v[84:85], v0 offset:14336
	v_cndmask_b32_e64 v114, 0, 1, s[0:1]
	v_cmp_ne_u32_e64 s[8:9], 1, v114
	s_andn2_b64 vcc, exec, s[0:1]
	s_cbranch_vccnz .Lh2_456
; template <bool FIRST, bool DOEXP = true>
; __device__ __forceinline__ void partialSM(f32x16& p0, f32x16& p1, float& m_reg, f32x16& negm, float& alpha, const bool track = true) {
;     ...
;   float pmax = p0[0];
; #pragma unroll
;   for (int r = 1; r < 16; ++r) pmax = fmaxf(pmax, p0[r]);
; #pragma unroll
;   for (int r = 0; r < 16; ++r) pmax = fmaxf(pmax, p1[r]);
;   { auto rr = __builtin_amdgcn_permlane32_swap(__float_as_uint(pmax), __float_as_uint(pmax), false, false);
;     pmax = fmaxf(__uint_as_float(rr[0]), __uint_as_float(rr[1])); }
;   if (!FIRST && __builtin_expect(__all(pmax <= THRL), 1)) { alpha = 1.f; }
;   else { const float dl = FIRST ? pmax : fmaxf(pmax, 0.f); m_reg += dl; alpha = FIRST ? 1.f : __builtin_amdgcn_exp2f(-dl);
; #pragma unroll
;     for (int r = 0; r < 16; ++r) { p0[r] -= dl; p1[r] -= dl; }
; #pragma unroll
;     for (int r = 0; r < 16; ++r) negm[r] = -m_reg;
;     asm volatile("" : "+v"(negm)); }
	v_max_f32_e32 v114, v132, v133
	v_max3_f32 v114, v114, v134, v135
	v_max3_f32 v114, v114, v136, v137
	v_max3_f32 v114, v114, v138, v139
	v_max3_f32 v114, v114, v140, v141
	v_max3_f32 v114, v114, v142, v143
	v_max3_f32 v114, v114, v144, v145
	v_max3_f32 v114, v114, v146, v147
	v_max3_f32 v114, v114, v98, v99
	v_max3_f32 v114, v114, v100, v101
	v_max3_f32 v114, v114, v102, v103
	v_max3_f32 v114, v114, v104, v105
	v_max3_f32 v114, v114, v106, v107
	v_max3_f32 v114, v114, v108, v109
	v_max3_f32 v114, v114, v110, v111
	v_max3_f32 v114, v114, v112, v113
	v_mov_b32_e32 v115, v114
	s_nop 1
	v_permlane32_swap_b32_e32 v114, v115
	v_max_f32_e32 v114, v114, v115
	v_cmp_ge_f32_e32 vcc, s69, v114
	s_cmp_eq_u64 vcc, exec
	v_mov_b32_e32 v130, 1.0
	s_cbranch_scc1 .Lh2_457
	v_max_f32_e32 v66, v114, v114
	v_max_f32_e32 v66, 0, v66
	v_exp_f32_e64 v130, -v66
	v_add_f32_e32 v222, v222, v66
	v_sub_f32_e32 v147, v147, v66
	v_sub_f32_e32 v146, v146, v66
	v_sub_f32_e32 v145, v145, v66
	v_sub_f32_e32 v144, v144, v66
	v_sub_f32_e32 v143, v143, v66
	v_sub_f32_e32 v142, v142, v66
	v_sub_f32_e32 v141, v141, v66
	v_sub_f32_e32 v140, v140, v66
	v_sub_f32_e32 v139, v139, v66
	v_sub_f32_e32 v138, v138, v66
	v_sub_f32_e32 v137, v137, v66
	v_sub_f32_e32 v136, v136, v66
	v_sub_f32_e32 v135, v135, v66
	v_sub_f32_e32 v134, v134, v66
	v_sub_f32_e32 v133, v133, v66
	v_sub_f32_e32 v132, v132, v66
	v_sub_f32_e32 v113, v113, v66
	v_sub_f32_e32 v112, v112, v66
	v_sub_f32_e32 v111, v111, v66
	v_sub_f32_e32 v110, v110, v66
	v_sub_f32_e32 v109, v109, v66
	v_sub_f32_e32 v108, v108, v66
	v_sub_f32_e32 v107, v107, v66
	v_sub_f32_e32 v106, v106, v66
	v_sub_f32_e32 v105, v105, v66
	v_sub_f32_e32 v104, v104, v66
	v_sub_f32_e32 v103, v103, v66
	v_sub_f32_e32 v102, v102, v66
	v_sub_f32_e32 v101, v101, v66
	v_sub_f32_e32 v100, v100, v66
	v_sub_f32_e32 v99, v99, v66
	v_sub_f32_e32 v98, v98, v66
	v_xor_b32_e32 v66, 0x80000000, v222
	v_mov_b32_e32 v67, v66
	v_mov_b32_e32 v68, v66
	v_mov_b32_e32 v69, v66
	v_mov_b32_e32 v70, v66
	v_mov_b32_e32 v71, v66
	v_mov_b32_e32 v72, v66
	v_mov_b32_e32 v73, v66
	v_mov_b32_e32 v74, v66
	v_mov_b32_e32 v75, v66
	v_mov_b32_e32 v76, v66
	v_mov_b32_e32 v77, v66
	v_mov_b32_e32 v78, v66
	v_mov_b32_e32 v79, v66
	v_mov_b32_e32 v80, v66
	v_mov_b32_e32 v81, v66
	s_branch .Lh2_457

; #define SBAR() __builtin_amdgcn_sched_barrier(0)
; __device__ __forceinline__ unsigned cvtpk(float lo, float hi) { unsigned r; asm volatile("v_cvt_pk_bf16_f32 %0, %1, %2" : "=v"(r) : "v"(lo), "v"(hi)); return r; }
; template <bool FIRST, bool DOEXP = true>
; __device__ __forceinline__ void partialSM(f32x16& p0, f32x16& p1, float& m_reg, f32x16& negm, float& alpha, const bool track = true) {
;     ...
;   float pmax = p0[0];
; #pragma unroll
;   for (int r = 1; r < 16; ++r) pmax = fmaxf(pmax, p0[r]);
; #pragma unroll
;   for (int r = 0; r < 16; ++r) pmax = fmaxf(pmax, p1[r]);
;   { auto rr = __builtin_amdgcn_permlane32_swap(__float_as_uint(pmax), __float_as_uint(pmax), false, false);
;     pmax = fmaxf(__uint_as_float(rr[0]), __uint_as_float(rr[1])); }
; __device__ __forceinline__ void qkt_fin(f32x16& n0, f32x16& n1, const bf16_t* Ks, const bf16x8* qr, const f32x16& negm, int r32, int hi, ...
;   float psa = 0.f, psb = 0.f; u32x4 wa, wb, wc, wd;
;     ...
; #pragma unroll
;   for (int d0 = 0; d0 < 8; ++d0) { int cb = (d0 * 16 + hi * 8) * 2;
;     bf16x8 b0 = *reinterpret_cast<const bf16x8*>((const char*)Ks + KSWZ(r32, cb));
;     bf16x8 b1 = *reinterpret_cast<const bf16x8*>((const char*)Ks + KSWZ(32 + r32, cb));
;     SBAR(); if (d0 == 0) n0 = __builtin_amdgcn_mfma_f32_32x32x16_bf16(b0, qr[0], negm, 0, 0, 0); else n0 = __builtin_amdgcn_mfma_f32_32x32x16_bf16(b0, qr[d0], n0, 0, 0, 0);
;     SBAR(); QF_CHUNK(2 * d0); SBAR();
;     if (d0 == 0) n1 = __builtin_amdgcn_mfma_f32_32x32x16_bf16(b1, qr[0], negm, 0, 0, 0); else n1 = __builtin_amdgcn_mfma_f32_32x32x16_bf16(b1, qr[d0], n1, 0, 0, 0);
;     SBAR(); QF_CHUNK(2 * d0 + 1); SBAR();
;     if (d0 == 7) { vf8_read<0>(vf0, vbv); SBAR(); } }
;     ...
;   psb += P1[15]; wd[3] = cvtpk(P1[14], P1[15]);
;   l_reg = l_reg * alpha + (psa + psb);
;   pa0 = *reinterpret_cast<bf16x8*>(&wa); pa1 = *reinterpret_cast<bf16x8*>(&wb); pa2 = *reinterpret_cast<bf16x8*>(&wc); pa3 = *reinterpret_cast<bf16x8*>(&wd);
; }
.Lh2_461:
	s_setprio 1
	s_waitcnt lgkmcnt(0)
	s_waitcnt vmcnt(0)
	s_barrier
	v_add_u32_e32 v208, s99, v236
	ds_read_b128 v[204:207], v208 offset:16384
	ds_read_b128 v[208:211], v208 offset:24576
	v_add_u32_e32 v252, s99, v237
	ds_read_b128 v[248:251], v252 offset:16384
	ds_read_b128 v[252:255], v252 offset:24576
	v_add_u32_e32 v203, s96, v235
	s_waitcnt lgkmcnt(3)
	v_mfma_f32_32x32x16_bf16 v[114:129], v[204:207], v[152:155], v[66:81]
	v_exp_f32_e32 v98, v98
	s_waitcnt lgkmcnt(2)
	v_mfma_f32_32x32x16_bf16 v[82:97], v[208:211], v[152:155], v[66:81]
	v_exp_f32_e32 v99, v99
	v_cvt_pk_bf16_f32 v132, v132, v133
	v_add_u32_e32 v208, s99, v238
	ds_read_b128 v[204:207], v208 offset:16384
	ds_read_b128 v[208:211], v208 offset:24576
	s_waitcnt lgkmcnt(3)
	v_mfma_f32_32x32x16_bf16 v[114:129], v[248:251], v[160:163], v[114:129]
	v_exp_f32_e32 v100, v100
	s_waitcnt lgkmcnt(2)
	v_mfma_f32_32x32x16_bf16 v[82:97], v[252:255], v[160:163], v[82:97]
	v_exp_f32_e32 v101, v101
	v_pk_add_f32 v[184:185], v[132:133], v[134:135]
	v_cvt_pk_bf16_f32 v133, v134, v135
	v_cvt_pk_bf16_f32 v196, v98, v99
	v_add_u32_e32 v252, s99, v239
	ds_read_b128 v[248:251], v252 offset:16384
	ds_read_b128 v[252:255], v252 offset:24576
	s_add_i32 s79, s98, s100
	s_add_i32 m0, s79, 0x4000
	s_add_i32 s79, s79, 0x6000
	global_load_lds_dwordx4 v[180:181], off
	s_waitcnt lgkmcnt(3)
	v_mfma_f32_32x32x16_bf16 v[114:129], v[204:207], v[148:151], v[114:129]
	v_exp_f32_e32 v102, v102
	v_pk_add_f32 v[186:187], v[98:99], v[100:101]
	s_waitcnt lgkmcnt(2)
	v_mfma_f32_32x32x16_bf16 v[82:97], v[208:211], v[148:151], v[82:97]
	v_exp_f32_e32 v103, v103
	v_pk_add_f32 v[184:185], v[184:185], v[136:137]
	v_cvt_pk_bf16_f32 v134, v136, v137
	v_cvt_pk_bf16_f32 v197, v100, v101
	v_add_u32_e32 v208, s99, v240
	ds_read_b128 v[204:207], v208 offset:16384
	ds_read_b128 v[208:211], v208 offset:24576
	s_mov_b32 m0, s79
	s_add_i32 s79, s98, s101
	global_load_lds_dwordx4 v[182:183], off
	s_waitcnt lgkmcnt(3)
	v_mfma_f32_32x32x16_bf16 v[114:129], v[248:251], v[156:159], v[114:129]
	v_exp_f32_e32 v104, v104
	v_pk_add_f32 v[186:187], v[186:187], v[102:103]
	s_waitcnt lgkmcnt(2)
	v_mfma_f32_32x32x16_bf16 v[82:97], v[252:255], v[156:159], v[82:97]
	v_exp_f32_e32 v105, v105
	v_pk_add_f32 v[184:185], v[184:185], v[138:139]
	v_cvt_pk_bf16_f32 v135, v138, v139
	v_cvt_pk_bf16_f32 v198, v102, v103
	v_add_u32_e32 v252, s99, v241
	ds_read_b128 v[248:251], v252 offset:16384
	ds_read_b128 v[252:255], v252 offset:24576
	s_mov_b32 m0, s79
	s_add_i32 s79, s79, 0x380
	global_load_lds_dwordx4 v[214:215], off
	s_waitcnt lgkmcnt(3)
	v_mfma_f32_32x32x16_bf16 v[114:129], v[204:207], v[168:171], v[114:129]
	v_exp_f32_e32 v106, v106
	v_pk_add_f32 v[186:187], v[186:187], v[104:105]
	s_waitcnt lgkmcnt(2)
	v_mfma_f32_32x32x16_bf16 v[82:97], v[208:211], v[168:171], v[82:97]
	v_exp_f32_e32 v107, v107
	v_pk_add_f32 v[184:185], v[184:185], v[140:141]
	v_cvt_pk_bf16_f32 v136, v140, v141
	v_cvt_pk_bf16_f32 v199, v104, v105
	v_add_u32_e32 v208, s99, v242
	ds_read_b128 v[204:207], v208 offset:16384
	ds_read_b128 v[208:211], v208 offset:24576
	s_mov_b32 m0, s79
	s_nop 0
	global_load_lds_dwordx4 v[214:215], off offset:128
	v_lshl_add_u64 v[180:181], v[180:181], 0, s[76:77]
	v_lshl_add_u64 v[182:183], v[182:183], 0, s[76:77]
	v_lshl_add_u64 v[214:215], v[214:215], 0, s[76:77]
	s_waitcnt lgkmcnt(3)
	v_mfma_f32_32x32x16_bf16 v[114:129], v[248:251], v[176:179], v[114:129]
	v_exp_f32_e32 v108, v108
	v_pk_add_f32 v[186:187], v[186:187], v[106:107]
	s_waitcnt lgkmcnt(2)
	v_mfma_f32_32x32x16_bf16 v[82:97], v[252:255], v[176:179], v[82:97]
	v_exp_f32_e32 v109, v109
	v_pk_add_f32 v[184:185], v[184:185], v[142:143]
	v_cvt_pk_bf16_f32 v137, v142, v143
	v_cvt_pk_bf16_f32 v140, v106, v107
	v_add_u32_e32 v252, s99, v243
	ds_read_b128 v[248:251], v252 offset:16384
	ds_read_b128 v[252:255], v252 offset:24576
	s_waitcnt lgkmcnt(3)
	v_mfma_f32_32x32x16_bf16 v[114:129], v[204:207], v[164:167], v[114:129]
	v_exp_f32_e32 v110, v110
	v_pk_add_f32 v[186:187], v[186:187], v[108:109]
	s_waitcnt lgkmcnt(2)
	v_mfma_f32_32x32x16_bf16 v[82:97], v[208:211], v[164:167], v[82:97]
	v_exp_f32_e32 v111, v111
	v_pk_add_f32 v[184:185], v[184:185], v[144:145]
	v_cvt_pk_bf16_f32 v138, v144, v145
	v_cvt_pk_bf16_f32 v141, v108, v109
	s_waitcnt lgkmcnt(1)
	v_mfma_f32_32x32x16_bf16 v[114:129], v[248:251], v[172:175], v[114:129]
	v_exp_f32_e32 v112, v112
	v_pk_add_f32 v[186:187], v[186:187], v[110:111]
	s_waitcnt lgkmcnt(0)
	v_mfma_f32_32x32x16_bf16 v[82:97], v[252:255], v[172:175], v[82:97]
	v_exp_f32_e32 v113, v113
	v_pk_add_f32 v[184:185], v[184:185], v[146:147]
	v_add_f32_e32 v201, v184, v185
	v_add_f32_e32 v202, v186, v187
	v_add_f32_e32 v202, v202, v112
	v_cvt_pk_bf16_f32 v139, v146, v147
	v_cvt_pk_bf16_f32 v142, v110, v111
	ds_read_b64_tr_b16 v[144:145], v203 offset:0
	ds_read_b64_tr_b16 v[146:147], v203 offset:2048
	s_nop 0
	ds_read_b64_tr_b16 v[106:107], v203 offset:4096
	ds_read_b64_tr_b16 v[108:109], v203 offset:6144
	ds_read_b64_tr_b16 v[102:103], v203 offset:8192
	ds_read_b64_tr_b16 v[104:105], v203 offset:10240
	ds_read_b64_tr_b16 v[98:99], v203 offset:12288
	ds_read_b64_tr_b16 v[100:101], v203 offset:14336
	v_cvt_pk_bf16_f32 v143, v112, v113
	s_and_b64 vcc, exec, s[8:9]
	v_mov_b32_e32 v200, 1.0
	s_cbranch_vccnz .Lh2_463
	v_max_f32_e32 v110, v114, v115
	v_max3_f32 v110, v110, v116, v117
	v_max3_f32 v110, v110, v118, v119
	v_max3_f32 v110, v110, v120, v121
	v_max3_f32 v110, v110, v122, v123
	v_max3_f32 v110, v110, v124, v125
	v_max3_f32 v110, v110, v126, v127
	v_max3_f32 v110, v110, v128, v129
	v_max3_f32 v110, v110, v82, v83
	v_max3_f32 v110, v110, v84, v85
	v_max3_f32 v110, v110, v86, v87
	v_max3_f32 v110, v110, v88, v89
	v_max3_f32 v110, v110, v90, v91
	v_max3_f32 v110, v110, v92, v93
	v_max3_f32 v110, v110, v94, v95
	v_max3_f32 v110, v110, v96, v97
	v_mov_b32_e32 v111, v110
	s_nop 1
	v_permlane32_swap_b32_e32 v110, v111
	v_max_f32_e32 v110, v110, v111
	v_cmp_ge_f32_e32 vcc, s69, v110
	s_cmp_eq_u64 vcc, exec
	v_mov_b32_e32 v200, 1.0
	s_cbranch_scc0 .Lh2_469

; #define SBAR() __builtin_amdgcn_sched_barrier(0)
; __device__ __forceinline__ unsigned cvtpk(float lo, float hi) { unsigned r; asm volatile("v_cvt_pk_bf16_f32 %0, %1, %2" : "=v"(r) : "v"(lo), "v"(hi)); return r; }
; template <bool FIRST, bool DOEXP = true>
; __device__ __forceinline__ void partialSM(f32x16& p0, f32x16& p1, float& m_reg, f32x16& negm, float& alpha, const bool track = true) {
;     ...
;   float pmax = p0[0];
; #pragma unroll
;   for (int r = 1; r < 16; ++r) pmax = fmaxf(pmax, p0[r]);
; #pragma unroll
;   for (int r = 0; r < 16; ++r) pmax = fmaxf(pmax, p1[r]);
;   { auto rr = __builtin_amdgcn_permlane32_swap(__float_as_uint(pmax), __float_as_uint(pmax), false, false);
;     pmax = fmaxf(__uint_as_float(rr[0]), __uint_as_float(rr[1])); }
; __device__ __forceinline__ void qkt_fin(f32x16& n0, f32x16& n1, const bf16_t* Ks, const bf16x8* qr, const f32x16& negm, int r32, int hi, ...
;   float psa = 0.f, psb = 0.f; u32x4 wa, wb, wc, wd;
;     ...
; #pragma unroll
;   for (int d0 = 0; d0 < 8; ++d0) { int cb = (d0 * 16 + hi * 8) * 2;
;     bf16x8 b0 = *reinterpret_cast<const bf16x8*>((const char*)Ks + KSWZ(r32, cb));
;     bf16x8 b1 = *reinterpret_cast<const bf16x8*>((const char*)Ks + KSWZ(32 + r32, cb));
;     SBAR(); if (d0 == 0) n0 = __builtin_amdgcn_mfma_f32_32x32x16_bf16(b0, qr[0], negm, 0, 0, 0); else n0 = __builtin_amdgcn_mfma_f32_32x32x16_bf16(b0, qr[d0], n0, 0, 0, 0);
;     SBAR(); QF_CHUNK(2 * d0); SBAR();
;     if (d0 == 0) n1 = __builtin_amdgcn_mfma_f32_32x32x16_bf16(b1, qr[0], negm, 0, 0, 0); else n1 = __builtin_amdgcn_mfma_f32_32x32x16_bf16(b1, qr[d0], n1, 0, 0, 0);
;     SBAR(); QF_CHUNK(2 * d0 + 1); SBAR();
;     if (d0 == 7) { vf8_read<0>(vf0, vbv); SBAR(); } }
;     ...
;   psb += P1[15]; wd[3] = cvtpk(P1[14], P1[15]);
;   l_reg = l_reg * alpha + (psa + psb);
;   pa0 = *reinterpret_cast<bf16x8*>(&wa); pa1 = *reinterpret_cast<bf16x8*>(&wb); pa2 = *reinterpret_cast<bf16x8*>(&wc); pa3 = *reinterpret_cast<bf16x8*>(&wd);
; }
.LBB0_470:
	s_setprio 0
	s_waitcnt vmcnt(0)
	s_mov_b32 s80, 0x18000
	s_mov_b32 s76, 0x10000
	v_add_u32_e32 v0, 0x18000, v235
	v_add3_u32 v98, s80, v234, v221
	ds_read_b128 v[130:133], v98 offset:16384
	ds_read_b128 v[134:137], v98 offset:24576
	v_add_u32_e32 v180, s76, v235
	s_waitcnt lgkmcnt(1)
	v_mfma_f32_32x32x16_bf16 v[98:113], v[130:133], v[152:155], v[66:81]
	v_exp_f32_e32 v82, v82
	v_add_f32_e32 v130, 0, v114
	v_mov_b32_e32 v131, v1
	s_waitcnt lgkmcnt(0)
	v_mfma_f32_32x32x16_bf16 v[66:81], v[134:137], v[152:155], v[66:81]
	v_exp_f32_e32 v83, v83
	v_add_f32_e32 v140, v115, v130
	v_add_f32_e32 v131, v131, v82
	v_cvt_pk_bf16_f32 v130, v114, v115
	v_add3_u32 v114, s80, v233, v221
	ds_read_b128 v[132:135], v114 offset:16384
	ds_read_b128 v[136:139], v114 offset:24576
	s_waitcnt lgkmcnt(1)
	v_mfma_f32_32x32x16_bf16 v[98:113], v[132:135], v[160:163], v[98:113]
	v_exp_f32_e32 v84, v84
	v_add_f32_e32 v114, v116, v140
	v_add_f32_e32 v115, v131, v83
	s_waitcnt lgkmcnt(0)
	v_mfma_f32_32x32x16_bf16 v[66:81], v[136:139], v[160:163], v[66:81]
	v_exp_f32_e32 v85, v85
	v_add_f32_e32 v132, v117, v114
	v_add_f32_e32 v133, v115, v84
	v_cvt_pk_bf16_f32 v131, v116, v117
	v_cvt_pk_bf16_f32 v134, v82, v83
	v_add3_u32 v135, s80, v230, v221
	ds_read_b128 v[114:117], v135 offset:16384
	ds_read_b128 v[136:139], v135 offset:24576
	s_waitcnt lgkmcnt(1)
	v_mfma_f32_32x32x16_bf16 v[98:113], v[114:117], v[148:151], v[98:113]
	v_exp_f32_e32 v86, v86
	v_add_f32_e32 v114, v118, v132
	v_add_f32_e32 v115, v133, v85
	s_waitcnt lgkmcnt(0)
	v_mfma_f32_32x32x16_bf16 v[66:81], v[136:139], v[148:151], v[66:81]
	v_exp_f32_e32 v87, v87
	v_add_f32_e32 v133, v119, v114
	v_add_f32_e32 v140, v115, v86
	v_cvt_pk_bf16_f32 v132, v118, v119
	v_cvt_pk_bf16_f32 v135, v84, v85
	v_add3_u32 v118, s80, v227, v221
	ds_read_b128 v[114:117], v118 offset:16384
	ds_read_b128 v[136:139], v118 offset:24576
	s_waitcnt lgkmcnt(1)
	v_mfma_f32_32x32x16_bf16 v[98:113], v[114:117], v[156:159], v[98:113]
	v_exp_f32_e32 v88, v88
	v_add_f32_e32 v114, v120, v133
	v_add_f32_e32 v115, v140, v87
	s_waitcnt lgkmcnt(0)
	v_mfma_f32_32x32x16_bf16 v[66:81], v[136:139], v[156:159], v[66:81]
	v_exp_f32_e32 v89, v89
	v_add_f32_e32 v137, v121, v114
	v_add_f32_e32 v138, v115, v88
	v_cvt_pk_bf16_f32 v133, v120, v121
	v_cvt_pk_bf16_f32 v136, v86, v87
	v_add3_u32 v118, s80, v226, v221
	ds_read_b128 v[114:117], v118 offset:16384
	ds_read_b128 v[118:121], v118 offset:24576
	s_waitcnt lgkmcnt(1)
	v_mfma_f32_32x32x16_bf16 v[98:113], v[114:117], v[168:171], v[98:113]
	v_exp_f32_e32 v90, v90
	v_add_f32_e32 v114, v122, v137
	v_add_f32_e32 v115, v138, v89
	s_waitcnt lgkmcnt(0)
	v_mfma_f32_32x32x16_bf16 v[66:81], v[118:121], v[168:171], v[66:81]
	v_exp_f32_e32 v91, v91
	v_add_f32_e32 v139, v123, v114
	v_add_f32_e32 v140, v115, v90
	v_cvt_pk_bf16_f32 v138, v122, v123
	v_cvt_pk_bf16_f32 v137, v88, v89
	v_add3_u32 v118, s80, v225, v221
	ds_read_b128 v[114:117], v118 offset:16384
	ds_read_b128 v[118:121], v118 offset:24576
	s_waitcnt lgkmcnt(1)
	v_mfma_f32_32x32x16_bf16 v[98:113], v[114:117], v[176:179], v[98:113]
	v_exp_f32_e32 v92, v92
	v_add_f32_e32 v114, v124, v139
	v_add_f32_e32 v115, v140, v91
	s_waitcnt lgkmcnt(0)
	v_mfma_f32_32x32x16_bf16 v[66:81], v[118:121], v[176:179], v[66:81]
	v_exp_f32_e32 v93, v93
	v_add_f32_e32 v122, v125, v114
	v_add_f32_e32 v123, v115, v92
	v_cvt_pk_bf16_f32 v139, v124, v125
	v_cvt_pk_bf16_f32 v142, v90, v91
	v_add3_u32 v118, s80, v224, v221
	ds_read_b128 v[114:117], v118 offset:16384
	ds_read_b128 v[118:121], v118 offset:24576
	s_waitcnt lgkmcnt(1)
	v_mfma_f32_32x32x16_bf16 v[98:113], v[114:117], v[164:167], v[98:113]
	v_exp_f32_e32 v94, v94
	v_add_f32_e32 v114, v126, v122
	v_add_f32_e32 v115, v123, v93
	s_waitcnt lgkmcnt(0)
	v_mfma_f32_32x32x16_bf16 v[66:81], v[118:121], v[164:167], v[66:81]
	v_exp_f32_e32 v95, v95
	v_add_f32_e32 v122, v127, v114
	v_add_f32_e32 v123, v115, v94
	v_cvt_pk_bf16_f32 v140, v126, v127
	v_cvt_pk_bf16_f32 v143, v92, v93
	v_add3_u32 v118, s80, v223, v221
	ds_read_b128 v[114:117], v118 offset:16384
	ds_read_b128 v[118:121], v118 offset:24576
	s_waitcnt lgkmcnt(1)
	v_mfma_f32_32x32x16_bf16 v[98:113], v[114:117], v[172:175], v[98:113]
	v_exp_f32_e32 v96, v96
	v_add_f32_e32 v114, v128, v122
	v_add_f32_e32 v115, v123, v95
	s_waitcnt lgkmcnt(0)
	v_mfma_f32_32x32x16_bf16 v[66:81], v[118:121], v[172:175], v[66:81]
	v_exp_f32_e32 v97, v97
	v_add_f32_e32 v150, v129, v114
	v_add_f32_e32 v151, v115, v96
	v_cvt_pk_bf16_f32 v141, v128, v129
	v_cvt_pk_bf16_f32 v144, v94, v95
	ds_read_b64_tr_b16 v[146:147], v180 offset:0
	ds_read_b64_tr_b16 v[148:149], v180 offset:0x800
	s_nop 0
	ds_read_b64_tr_b16 v[90:91], v180 offset:0x1000
	ds_read_b64_tr_b16 v[92:93], v180 offset:0x1800
	ds_read_b64_tr_b16 v[86:87], v180 offset:0x2000
	ds_read_b64_tr_b16 v[88:89], v180 offset:0x2800
	ds_read_b64_tr_b16 v[82:83], v180 offset:0x3000
	ds_read_b64_tr_b16 v[84:85], v180 offset:0x3800
	v_cvt_pk_bf16_f32 v145, v96, v97
	s_and_b64 vcc, exec, s[8:9]
	v_mov_b32_e32 v94, 1.0
	s_cbranch_vccnz .LBB0_472
	v_max_f32_e32 v94, v98, v99
	v_max3_f32 v94, v94, v100, v101
	v_max3_f32 v94, v94, v102, v103
	v_max3_f32 v94, v94, v104, v105
	v_max3_f32 v94, v94, v106, v107
	v_max3_f32 v94, v94, v108, v109
	v_max3_f32 v94, v94, v110, v111
	v_max3_f32 v94, v94, v112, v113
	v_max3_f32 v94, v94, v66, v67
	v_max3_f32 v94, v94, v68, v69
	v_max3_f32 v94, v94, v70, v71
	v_max3_f32 v94, v94, v72, v73
	v_max3_f32 v94, v94, v74, v75
	v_max3_f32 v94, v94, v76, v77
	v_max3_f32 v94, v94, v78, v79
	v_max3_f32 v94, v94, v80, v81
	v_mov_b32_e32 v95, v94
	s_nop 1
	v_permlane32_swap_b32_e32 v94, v95
	v_max_f32_e32 v95, v95, v95
	v_max_f32_e32 v94, v94, v94
	v_max_f32_e32 v95, v94, v95
	v_cmp_ge_f32_e32 vcc, s69, v95
	s_cmp_eq_u64 vcc, exec
	v_mov_b32_e32 v94, 1.0
	s_cbranch_scc0 .LBB0_478
